# hand-written P5 up-projection epilogue body: conv via v_fmac_f32_dpp (row_shr/row_shl + masked-coefficient row_ror for the cross-block neighbour), packed SiLU arithmetic, RAW edge rows as dwordx4 stor
# speedup vs baseline: 1.0114x; 1.0114x over previous
; __device__ __forceinline__ float row_rstd(const float* ssp, int row, int fq) {
;     const f32x4 a = *(const f32x4*)(ssp + (size_t)row * 32 + 8 * fq), b = *(const f32x4*)(ssp + (size_t)row * 32 + 8 * fq + 4);
;     float s = ((a[0] + a[1]) + (a[2] + a[3])) + ((b[0] + b[1]) + (b[2] + b[3]));
;     s += __shfl_xor(s, 16); s += __shfl_xor(s, 32);
;     return __builtin_amdgcn_rsqf(s * (1.0f / 2048.0f) + 1e-6f);
;     __device__ __forceinline__ void operator()(f32x4 (&acc)[2][2][4][2], const Unit& u, int wr, int wc, int fr, int fq) const {
;     ...
;             for (int m = 0; m < 4; ++m) { const float rstd = row_rstd(ss, row0 + ai * HALF + m * 16, fq);
; #pragma unroll
;                 for (int bj = 0; bj < 2; ++bj) { acc[ai][bj][m][0] *= rstd; acc[ai][bj][m][1] *= rstd; } }
; #pragma unroll
;         for (int n = 0; n < 2; ++n) {
;             const int j4 = u.pn * 128 + wc * 32 + 8 * fq + 4 * n;
;             f32x4 kc[2][3], bc[2];
; #pragma unroll
;             for (int bj = 0; bj < 2; ++bj) { bc[bj] = *(const f32x4*)(cb + bj * FF + j4);
; #pragma unroll
;                 for (int w = 0; w < 3; ++w) kc[bj][w] = *(const f32x4*)(ck + w * NUP + bj * FF + j4); }
.LBB0_755:
	s_waitcnt vmcnt(14)
	v_add_f32_e32 v174, v174, v175
	v_add_f32_e32 v176, v176, v177
	v_add_f32_e32 v178, v178, v179
	v_add_f32_e32 v180, v180, v181
	v_add_f32_e32 v174, v174, v176
	v_add_f32_e32 v178, v178, v180
	v_add_f32_e32 v130, v174, v178
	s_waitcnt vmcnt(12)
	v_add_f32_e32 v182, v182, v183
	v_add_f32_e32 v184, v184, v185
	v_add_f32_e32 v186, v186, v187
	v_add_f32_e32 v188, v188, v189
	v_add_f32_e32 v182, v182, v184
	v_add_f32_e32 v186, v186, v188
	v_add_f32_e32 v132, v182, v186
	s_waitcnt vmcnt(10)
	v_add_f32_e32 v190, v190, v191
	v_add_f32_e32 v192, v192, v193
	v_add_f32_e32 v194, v194, v195
	v_add_f32_e32 v196, v196, v197
	v_add_f32_e32 v190, v190, v192
	v_add_f32_e32 v194, v194, v196
	v_add_f32_e32 v134, v190, v194
	s_waitcnt vmcnt(8)
	v_add_f32_e32 v198, v198, v199
	v_add_f32_e32 v200, v200, v201
	v_add_f32_e32 v202, v202, v203
	v_add_f32_e32 v204, v204, v205
	v_add_f32_e32 v198, v198, v200
	v_add_f32_e32 v202, v202, v204
	v_add_f32_e32 v136, v198, v202
	s_waitcnt vmcnt(6)
	v_add_f32_e32 v206, v206, v207
	v_add_f32_e32 v208, v208, v209
	v_add_f32_e32 v210, v210, v211
	v_add_f32_e32 v212, v212, v213
	v_add_f32_e32 v206, v206, v208
	v_add_f32_e32 v210, v210, v212
	v_add_f32_e32 v138, v206, v210
	s_waitcnt vmcnt(4)
	v_add_f32_e32 v214, v214, v215
	v_add_f32_e32 v216, v216, v217
	v_add_f32_e32 v218, v218, v219
	v_add_f32_e32 v220, v220, v221
	v_add_f32_e32 v214, v214, v216
	v_add_f32_e32 v218, v218, v220
	v_add_f32_e32 v140, v214, v218
	s_waitcnt vmcnt(2)
	v_add_f32_e32 v222, v222, v223
	v_add_f32_e32 v224, v224, v225
	v_add_f32_e32 v226, v226, v227
	v_add_f32_e32 v228, v228, v229
	v_add_f32_e32 v222, v222, v224
	v_add_f32_e32 v226, v226, v228
	v_add_f32_e32 v142, v222, v226
	s_waitcnt vmcnt(0)
	v_add_f32_e32 v230, v230, v231
	v_add_f32_e32 v232, v232, v233
	v_add_f32_e32 v234, v234, v235
	v_add_f32_e32 v236, v236, v237
	v_add_f32_e32 v230, v230, v232
	v_add_f32_e32 v234, v234, v236
	v_add_f32_e32 v144, v230, v234
	v_lshl_or_b32 v242, s16, 7, v250
	v_lshlrev_b32_e32 v252, 1, v242
	v_lshlrev_b32_e32 v242, 2, v242
	v_add_u32_e32 v131, 0x5600, v242
	v_add_u32_e32 v133, 0xac00, v242
	v_add_u32_e32 v135, 0x10200, v242
	v_add_u32_e32 v137, 0x15800, v242
	v_add_u32_e32 v139, 0x1ae00, v242
	global_load_dwordx4 v[182:185], v242, s[18:19]
	global_load_dwordx4 v[186:189], v133, s[18:19]
	global_load_dwordx4 v[190:193], v137, s[18:19]
	global_load_dwordx4 v[194:197], v242, s[20:21]
	global_load_dwordx4 v[198:201], v131, s[18:19]
	global_load_dwordx4 v[202:205], v135, s[18:19]
	global_load_dwordx4 v[206:209], v139, s[18:19]
	global_load_dwordx4 v[210:213], v131, s[20:21]
	ds_bpermute_b32 v174, v238, v130
	ds_bpermute_b32 v175, v238, v132
	ds_bpermute_b32 v176, v238, v134
	ds_bpermute_b32 v177, v238, v136
	ds_bpermute_b32 v178, v238, v138
	ds_bpermute_b32 v179, v238, v140
	ds_bpermute_b32 v180, v238, v142
	ds_bpermute_b32 v181, v238, v144
	s_waitcnt lgkmcnt(0)
	v_add_f32_e32 v130, v130, v174
	v_add_f32_e32 v132, v132, v175
	v_add_f32_e32 v134, v134, v176
	v_add_f32_e32 v136, v136, v177
	v_add_f32_e32 v138, v138, v178
	v_add_f32_e32 v140, v140, v179
	v_add_f32_e32 v142, v142, v180
	v_add_f32_e32 v144, v144, v181
	ds_bpermute_b32 v174, v239, v130
	ds_bpermute_b32 v175, v239, v132
	ds_bpermute_b32 v176, v239, v134
	ds_bpermute_b32 v177, v239, v136
	ds_bpermute_b32 v178, v239, v138
	ds_bpermute_b32 v179, v239, v140
	ds_bpermute_b32 v180, v239, v142
	ds_bpermute_b32 v181, v239, v144
	s_waitcnt lgkmcnt(0)
	v_add_f32_e32 v130, v130, v174
	v_add_f32_e32 v132, v132, v175
	v_add_f32_e32 v134, v134, v176
	v_add_f32_e32 v136, v136, v177
	v_add_f32_e32 v138, v138, v178
	v_add_f32_e32 v140, v140, v179
	v_add_f32_e32 v142, v142, v180
	v_add_f32_e32 v144, v144, v181
	v_fmamk_f32 v130, v130, 0x3a000000, v243
	v_fmamk_f32 v132, v132, 0x3a000000, v243
	v_fmamk_f32 v134, v134, 0x3a000000, v243
	v_fmamk_f32 v136, v136, 0x3a000000, v243
	v_fmamk_f32 v138, v138, 0x3a000000, v243
	v_fmamk_f32 v140, v140, 0x3a000000, v243
	v_fmamk_f32 v142, v142, 0x3a000000, v243
	v_fmamk_f32 v144, v144, 0x3a000000, v243
	v_rsq_f32_e32 v130, v130
	v_rsq_f32_e32 v132, v132
	v_rsq_f32_e32 v134, v134
	v_rsq_f32_e32 v136, v136
	v_rsq_f32_e32 v138, v138
	v_rsq_f32_e32 v140, v140
	v_rsq_f32_e32 v142, v142
	v_rsq_f32_e32 v144, v144
	s_nop 0
	v_pk_mul_f32 v[126:127], v[126:127], v[130:131] op_sel_hi:[1,0]
	v_pk_mul_f32 v[128:129], v[128:129], v[130:131] op_sel_hi:[1,0]
	v_pk_mul_f32 v[62:63], v[62:63], v[130:131] op_sel_hi:[1,0]
	v_pk_mul_f32 v[64:65], v[64:65], v[130:131] op_sel_hi:[1,0]
	v_pk_mul_f32 v[122:123], v[122:123], v[130:131] op_sel_hi:[1,0]
	v_pk_mul_f32 v[124:125], v[124:125], v[130:131] op_sel_hi:[1,0]
	v_pk_mul_f32 v[54:55], v[54:55], v[130:131] op_sel_hi:[1,0]
	v_pk_mul_f32 v[56:57], v[56:57], v[130:131] op_sel_hi:[1,0]
	v_pk_mul_f32 v[118:119], v[118:119], v[132:133] op_sel_hi:[1,0]
	v_pk_mul_f32 v[120:121], v[120:121], v[132:133] op_sel_hi:[1,0]
	v_pk_mul_f32 v[58:59], v[58:59], v[132:133] op_sel_hi:[1,0]
	v_pk_mul_f32 v[60:61], v[60:61], v[132:133] op_sel_hi:[1,0]
	v_pk_mul_f32 v[114:115], v[114:115], v[132:133] op_sel_hi:[1,0]
	v_pk_mul_f32 v[116:117], v[116:117], v[132:133] op_sel_hi:[1,0]
	v_pk_mul_f32 v[50:51], v[50:51], v[132:133] op_sel_hi:[1,0]
	v_pk_mul_f32 v[52:53], v[52:53], v[132:133] op_sel_hi:[1,0]
	v_pk_mul_f32 v[110:111], v[110:111], v[134:135] op_sel_hi:[1,0]
	v_pk_mul_f32 v[112:113], v[112:113], v[134:135] op_sel_hi:[1,0]
	v_pk_mul_f32 v[46:47], v[46:47], v[134:135] op_sel_hi:[1,0]
	v_pk_mul_f32 v[48:49], v[48:49], v[134:135] op_sel_hi:[1,0]
	v_pk_mul_f32 v[102:103], v[102:103], v[134:135] op_sel_hi:[1,0]
	v_pk_mul_f32 v[104:105], v[104:105], v[134:135] op_sel_hi:[1,0]
; __device__ __forceinline__ unsigned cvt_pk_bf16(float lo, float hi) { unsigned r; asm volatile("v_cvt_pk_bf16_f32 %0, %1, %2" : "=v"(r) : "v"(lo), "v"(hi)); return r; }
;     __device__ __forceinline__ void operator()(f32x4 (&acc)[2][2][4][2], const Unit& u, int wr, int wc, int fr, int fq) const {
;     ...
;             for (int m = 0; m < 4; ++m) { const float rstd = row_rstd(ss, row0 + ai * HALF + m * 16, fq);
; #pragma unroll
;                 for (int bj = 0; bj < 2; ++bj) { acc[ai][bj][m][0] *= rstd; acc[ai][bj][m][1] *= rstd; } }
;     ...
;                     if (m == 0 && fr < 2) {
; #pragma unroll
;                         for (int bj = 0; bj < 2; ++bj) { const f32x4 v = acc[ai][bj][0][n]; u32x2 w; w.x = cvt_pk_bf16(v[0], v[1]); w.y = cvt_pk_bf16(v[2], v[3]); *(u32x2*)(RAW + ((size_t)(grp * 4 + fr)) * NUP + bj * FF + j4) = w; } }
;                     if (m == 3 && fr >= 14) {
; #pragma unroll
;                         for (int bj = 0; bj < 2; ++bj) { const f32x4 v = acc[ai][bj][3][n]; u32x2 w; w.x = cvt_pk_bf16(v[0], v[1]); w.y = cvt_pk_bf16(v[2], v[3]); *(u32x2*)(RAW + ((size_t)(grp * 4 + 2 + (fr - 14))) * NUP + bj * FF + j4) = w; } }
	v_pk_mul_f32 v[38:39], v[38:39], v[134:135] op_sel_hi:[1,0]
	v_pk_mul_f32 v[40:41], v[40:41], v[134:135] op_sel_hi:[1,0]
	v_pk_mul_f32 v[106:107], v[106:107], v[136:137] op_sel_hi:[1,0]
	v_pk_mul_f32 v[108:109], v[108:109], v[136:137] op_sel_hi:[1,0]
	v_pk_mul_f32 v[42:43], v[42:43], v[136:137] op_sel_hi:[1,0]
	v_pk_mul_f32 v[44:45], v[44:45], v[136:137] op_sel_hi:[1,0]
	v_pk_mul_f32 v[98:99], v[98:99], v[136:137] op_sel_hi:[1,0]
	v_pk_mul_f32 v[100:101], v[100:101], v[136:137] op_sel_hi:[1,0]
	v_pk_mul_f32 v[34:35], v[34:35], v[136:137] op_sel_hi:[1,0]
	v_pk_mul_f32 v[36:37], v[36:37], v[136:137] op_sel_hi:[1,0]
	v_pk_mul_f32 v[94:95], v[94:95], v[138:139] op_sel_hi:[1,0]
	v_pk_mul_f32 v[96:97], v[96:97], v[138:139] op_sel_hi:[1,0]
	v_pk_mul_f32 v[30:31], v[30:31], v[138:139] op_sel_hi:[1,0]
	v_pk_mul_f32 v[32:33], v[32:33], v[138:139] op_sel_hi:[1,0]
	v_pk_mul_f32 v[86:87], v[86:87], v[138:139] op_sel_hi:[1,0]
	v_pk_mul_f32 v[88:89], v[88:89], v[138:139] op_sel_hi:[1,0]
	v_pk_mul_f32 v[22:23], v[22:23], v[138:139] op_sel_hi:[1,0]
	v_pk_mul_f32 v[24:25], v[24:25], v[138:139] op_sel_hi:[1,0]
	v_pk_mul_f32 v[90:91], v[90:91], v[140:141] op_sel_hi:[1,0]
	v_pk_mul_f32 v[92:93], v[92:93], v[140:141] op_sel_hi:[1,0]
	v_pk_mul_f32 v[26:27], v[26:27], v[140:141] op_sel_hi:[1,0]
	v_pk_mul_f32 v[28:29], v[28:29], v[140:141] op_sel_hi:[1,0]
	v_pk_mul_f32 v[82:83], v[82:83], v[140:141] op_sel_hi:[1,0]
	v_pk_mul_f32 v[84:85], v[84:85], v[140:141] op_sel_hi:[1,0]
	v_pk_mul_f32 v[18:19], v[18:19], v[140:141] op_sel_hi:[1,0]
	v_pk_mul_f32 v[20:21], v[20:21], v[140:141] op_sel_hi:[1,0]
	v_pk_mul_f32 v[78:79], v[78:79], v[142:143] op_sel_hi:[1,0]
	v_pk_mul_f32 v[80:81], v[80:81], v[142:143] op_sel_hi:[1,0]
	v_pk_mul_f32 v[14:15], v[14:15], v[142:143] op_sel_hi:[1,0]
	v_pk_mul_f32 v[16:17], v[16:17], v[142:143] op_sel_hi:[1,0]
	v_pk_mul_f32 v[70:71], v[70:71], v[142:143] op_sel_hi:[1,0]
	v_pk_mul_f32 v[72:73], v[72:73], v[142:143] op_sel_hi:[1,0]
	v_pk_mul_f32 v[6:7], v[6:7], v[142:143] op_sel_hi:[1,0]
	v_pk_mul_f32 v[8:9], v[8:9], v[142:143] op_sel_hi:[1,0]
	v_pk_mul_f32 v[74:75], v[74:75], v[144:145] op_sel_hi:[1,0]
	v_pk_mul_f32 v[76:77], v[76:77], v[144:145] op_sel_hi:[1,0]
	v_pk_mul_f32 v[10:11], v[10:11], v[144:145] op_sel_hi:[1,0]
	v_pk_mul_f32 v[12:13], v[12:13], v[144:145] op_sel_hi:[1,0]
	v_pk_mul_f32 v[66:67], v[66:67], v[144:145] op_sel_hi:[1,0]
	v_pk_mul_f32 v[68:69], v[68:69], v[144:145] op_sel_hi:[1,0]
	v_pk_mul_f32 v[2:3], v[2:3], v[144:145] op_sel_hi:[1,0]
	v_pk_mul_f32 v[4:5], v[4:5], v[144:145] op_sel_hi:[1,0]
	s_mov_b32 s34, 0xbfb8aa3b
	s_mov_b32 s35, 0xbfb8aa3b
	s_mov_b32 s36, 1.0
	s_mov_b32 s37, 1.0
	v_lshl_add_u32 v238, s12, 8, v247
	v_mul_u32_u24_e32 v238, 0x2b00, v238
	v_add_u32_e32 v238, v238, v252
	s_lshl_b32 s13, s12, 4
	s_add_i32 s13, s13, s92
	v_add_u32_e32 v253, s13, v246
	v_mul_u32_u24_e32 v253, 0x5600, v253
	v_add_u32_e32 v253, v253, v252
	v_add_u32_e32 v239, 0x2b00, v253
	v_cvt_pk_bf16_f32 v230, v126, v127
	v_cvt_pk_bf16_f32 v231, v128, v129
	v_cvt_pk_bf16_f32 v232, v62, v63
	v_cvt_pk_bf16_f32 v233, v64, v65
	s_and_saveexec_b64 s[16:17], s[46:47]
	global_store_dwordx4 v253, v[230:233], s[54:55]
	s_or_b64 exec, exec, s[16:17]
	v_cvt_pk_bf16_f32 v234, v122, v123
	v_cvt_pk_bf16_f32 v235, v124, v125
	v_cvt_pk_bf16_f32 v236, v54, v55
	v_cvt_pk_bf16_f32 v237, v56, v57
	s_and_saveexec_b64 s[16:17], s[46:47]
	global_store_dwordx4 v239, v[234:237], s[54:55]
	s_or_b64 exec, exec, s[16:17]
	v_add_u32_e32 v253, s13, v246
	v_add_u32_e32 v253, 8, v253
	v_mul_u32_u24_e32 v253, 0x5600, v253
	v_add_u32_e32 v253, v253, v252
	v_add_u32_e32 v239, 0x2b00, v253
	v_cvt_pk_bf16_f32 v214, v94, v95
	v_cvt_pk_bf16_f32 v215, v96, v97
	v_cvt_pk_bf16_f32 v216, v30, v31
	v_cvt_pk_bf16_f32 v217, v32, v33
	s_and_saveexec_b64 s[16:17], s[46:47]
	global_store_dwordx4 v253, v[214:217], s[54:55]
	s_or_b64 exec, exec, s[16:17]
	v_cvt_pk_bf16_f32 v218, v86, v87
	v_cvt_pk_bf16_f32 v219, v88, v89
	v_cvt_pk_bf16_f32 v220, v22, v23
	v_cvt_pk_bf16_f32 v221, v24, v25
	s_and_saveexec_b64 s[16:17], s[46:47]
	global_store_dwordx4 v239, v[218:221], s[54:55]
	s_or_b64 exec, exec, s[16:17]
	v_add_u32_e32 v253, s13, v249
	v_mul_u32_u24_e32 v253, 0x5600, v253
	v_add_u32_e32 v253, v253, v252
	v_add_u32_e32 v239, 0x2b00, v253
	v_cvt_pk_bf16_f32 v230, v106, v107
	v_cvt_pk_bf16_f32 v231, v108, v109
	v_cvt_pk_bf16_f32 v232, v42, v43
	v_cvt_pk_bf16_f32 v233, v44, v45
	s_and_saveexec_b64 s[16:17], s[48:49]
	global_store_dwordx4 v253, v[230:233], s[54:55]
	s_or_b64 exec, exec, s[16:17]
	v_cvt_pk_bf16_f32 v234, v98, v99
	v_cvt_pk_bf16_f32 v235, v100, v101
	v_cvt_pk_bf16_f32 v236, v34, v35
	v_cvt_pk_bf16_f32 v237, v36, v37
	s_and_saveexec_b64 s[16:17], s[48:49]
	global_store_dwordx4 v239, v[234:237], s[54:55]
	s_or_b64 exec, exec, s[16:17]
	v_add_u32_e32 v253, s13, v249
	v_add_u32_e32 v253, 8, v253
	v_mul_u32_u24_e32 v253, 0x5600, v253
	v_add_u32_e32 v253, v253, v252
	v_add_u32_e32 v239, 0x2b00, v253
	v_cvt_pk_bf16_f32 v214, v74, v75
	v_cvt_pk_bf16_f32 v215, v76, v77
	v_cvt_pk_bf16_f32 v216, v10, v11
	v_cvt_pk_bf16_f32 v217, v12, v13
	s_and_saveexec_b64 s[16:17], s[48:49]
	global_store_dwordx4 v253, v[214:217], s[54:55]
	s_or_b64 exec, exec, s[16:17]
	v_cvt_pk_bf16_f32 v218, v66, v67
	v_cvt_pk_bf16_f32 v219, v68, v69
	v_cvt_pk_bf16_f32 v220, v2, v3
	v_cvt_pk_bf16_f32 v221, v4, v5
	s_and_saveexec_b64 s[16:17], s[48:49]
	global_store_dwordx4 v239, v[218:221], s[54:55]
	s_or_b64 exec, exec, s[16:17]
	s_waitcnt vmcnt(8)
; __device__ __forceinline__ unsigned cvt_pk_bf16(float lo, float hi) { unsigned r; asm volatile("v_cvt_pk_bf16_f32 %0, %1, %2" : "=v"(r) : "v"(lo), "v"(hi)); return r; }
; __device__ __forceinline__ float sigmoid_f(float x) { return fast_rcp(1.0f + fast_exp2(-1.4426950409f * x)); }
;     __device__ __forceinline__ void operator()(f32x4 (&acc)[2][2][4][2], const Unit& u, int wr, int wc, int fr, int fq) const {
;     ...
;                         const f32x4 cur = acc[ai][bj][m][n], lo = acc[ai][bj][m > 0 ? m - 1 : 0][n], hi = acc[ai][bj][m < 3 ? m + 1 : 3][n];
;                         f32x4 pv, nv;
; #pragma unroll
;                         for (int idx = 0; idx < 4; ++idx) {
;                             const float y = (fr == 15) ? lo[idx] : cur[idx], z = (fr == 0) ? hi[idx] : cur[idx];
;                             pv[idx] = __int_as_float(__builtin_amdgcn_update_dpp(0, __float_as_int(y), 0x121, 0xf, 0xf, false));
;                             nv[idx] = __int_as_float(__builtin_amdgcn_update_dpp(0, __float_as_int(z), 0x12f, 0xf, 0xf, false));
;                         }
;                         cv[bj] = kc[bj][0] * pv + kc[bj][1] * cur + kc[bj][2] * nv + bc[bj];
;                     }
;                     const int row = row0 + ai * HALF + m * 16;
;                     const bool edge = (m == 0 && fr == 0) || (m == 3 && fr == 15);
;                     if (!edge) { const f32x4 gt = cv[0], vl = cv[1];
;                         u32x2 w; w.x = cvt_pk_bf16(gt[0] * sigmoid_f(gt[0]) * vl[0], gt[1] * sigmoid_f(gt[1]) * vl[1]); w.y = cvt_pk_bf16(gt[2] * sigmoid_f(gt[2]) * vl[2], gt[3] * sigmoid_f(gt[3]) * vl[3]);
;                         *(u32x2*)(ACT + (size_t)row * FF + j4) = w; }
	v_cndmask_b32_e64 v214, 0, v182, s[42:43]
	v_cndmask_b32_e64 v215, 0, v183, s[42:43]
	v_cndmask_b32_e64 v216, 0, v184, s[42:43]
	v_cndmask_b32_e64 v217, 0, v185, s[42:43]
	v_cndmask_b32_e64 v218, 0, v198, s[42:43]
	v_cndmask_b32_e64 v219, 0, v199, s[42:43]
	v_cndmask_b32_e64 v220, 0, v200, s[42:43]
	v_cndmask_b32_e64 v221, 0, v201, s[42:43]
	v_cndmask_b32_e64 v222, 0, v190, s[38:39]
	v_cndmask_b32_e64 v223, 0, v191, s[38:39]
	v_cndmask_b32_e64 v224, 0, v192, s[38:39]
	v_cndmask_b32_e64 v225, 0, v193, s[38:39]
	v_cndmask_b32_e64 v226, 0, v206, s[38:39]
	v_cndmask_b32_e64 v227, 0, v207, s[38:39]
	v_cndmask_b32_e64 v228, 0, v208, s[38:39]
	v_cndmask_b32_e64 v229, 0, v209, s[38:39]
	v_pk_fma_f32 v[230:231], v[126:127], v[186:187], v[194:195]
	v_pk_fma_f32 v[232:233], v[128:129], v[188:189], v[196:197]
	v_pk_fma_f32 v[234:235], v[122:123], v[202:203], v[210:211]
	v_pk_fma_f32 v[236:237], v[124:125], v[204:205], v[212:213]
	v_fmac_f32_dpp v230, v126, v182 row_shr:1 row_mask:0xf bank_mask:0xf
	v_fmac_f32_dpp v231, v127, v183 row_shr:1 row_mask:0xf bank_mask:0xf
	v_fmac_f32_dpp v232, v128, v184 row_shr:1 row_mask:0xf bank_mask:0xf
	v_fmac_f32_dpp v233, v129, v185 row_shr:1 row_mask:0xf bank_mask:0xf
	v_fmac_f32_dpp v234, v122, v198 row_shr:1 row_mask:0xf bank_mask:0xf
	v_fmac_f32_dpp v235, v123, v199 row_shr:1 row_mask:0xf bank_mask:0xf
	v_fmac_f32_dpp v236, v124, v200 row_shr:1 row_mask:0xf bank_mask:0xf
	v_fmac_f32_dpp v237, v125, v201 row_shr:1 row_mask:0xf bank_mask:0xf
	v_fmac_f32_dpp v230, v126, v190 row_shl:1 row_mask:0xf bank_mask:0xf
	v_fmac_f32_dpp v231, v127, v191 row_shl:1 row_mask:0xf bank_mask:0xf
	v_fmac_f32_dpp v232, v128, v192 row_shl:1 row_mask:0xf bank_mask:0xf
	v_fmac_f32_dpp v233, v129, v193 row_shl:1 row_mask:0xf bank_mask:0xf
	v_fmac_f32_dpp v234, v122, v206 row_shl:1 row_mask:0xf bank_mask:0xf
	v_fmac_f32_dpp v235, v123, v207 row_shl:1 row_mask:0xf bank_mask:0xf
	v_fmac_f32_dpp v236, v124, v208 row_shl:1 row_mask:0xf bank_mask:0xf
	v_fmac_f32_dpp v237, v125, v209 row_shl:1 row_mask:0xf bank_mask:0xf
	v_fmac_f32_dpp v230, v118, v222 row_ror:15 row_mask:0xf bank_mask:0xf
	v_fmac_f32_dpp v231, v119, v223 row_ror:15 row_mask:0xf bank_mask:0xf
	v_fmac_f32_dpp v232, v120, v224 row_ror:15 row_mask:0xf bank_mask:0xf
	v_fmac_f32_dpp v233, v121, v225 row_ror:15 row_mask:0xf bank_mask:0xf
	v_fmac_f32_dpp v234, v114, v226 row_ror:15 row_mask:0xf bank_mask:0xf
	v_fmac_f32_dpp v235, v115, v227 row_ror:15 row_mask:0xf bank_mask:0xf
	v_fmac_f32_dpp v236, v116, v228 row_ror:15 row_mask:0xf bank_mask:0xf
	v_fmac_f32_dpp v237, v117, v229 row_ror:15 row_mask:0xf bank_mask:0xf
	v_pk_mul_f32 v[174:175], v[230:231], s[34:35]
	v_pk_mul_f32 v[176:177], v[232:233], s[34:35]
	v_exp_f32_e32 v174, v174
	v_exp_f32_e32 v175, v175
	v_exp_f32_e32 v176, v176
	v_exp_f32_e32 v177, v177
	v_pk_add_f32 v[174:175], v[174:175], s[36:37]
	v_pk_add_f32 v[176:177], v[176:177], s[36:37]
	v_rcp_f32_e32 v174, v174
	v_rcp_f32_e32 v175, v175
	v_rcp_f32_e32 v176, v176
	v_rcp_f32_e32 v177, v177
	v_pk_mul_f32 v[174:175], v[230:231], v[174:175]
	v_pk_mul_f32 v[176:177], v[232:233], v[176:177]
	v_pk_mul_f32 v[174:175], v[174:175], v[234:235]
	v_pk_mul_f32 v[176:177], v[176:177], v[236:237]
	v_cvt_pk_bf16_f32 v178, v174, v175
	v_cvt_pk_bf16_f32 v179, v176, v177
	s_and_saveexec_b64 s[16:17], s[44:45]
	global_store_dwordx2 v238, v[178:179], s[30:31]
	s_or_b64 exec, exec, s[16:17]
	v_pk_fma_f32 v[230:231], v[118:119], v[186:187], v[194:195]
	v_pk_fma_f32 v[232:233], v[120:121], v[188:189], v[196:197]
	v_pk_fma_f32 v[234:235], v[114:115], v[202:203], v[210:211]
	v_pk_fma_f32 v[236:237], v[116:117], v[204:205], v[212:213]
	v_fmac_f32_dpp v230, v118, v182 row_shr:1 row_mask:0xf bank_mask:0xf
	v_fmac_f32_dpp v231, v119, v183 row_shr:1 row_mask:0xf bank_mask:0xf
	v_fmac_f32_dpp v232, v120, v184 row_shr:1 row_mask:0xf bank_mask:0xf
	v_fmac_f32_dpp v233, v121, v185 row_shr:1 row_mask:0xf bank_mask:0xf
	v_fmac_f32_dpp v234, v114, v198 row_shr:1 row_mask:0xf bank_mask:0xf
	v_fmac_f32_dpp v235, v115, v199 row_shr:1 row_mask:0xf bank_mask:0xf
	v_fmac_f32_dpp v236, v116, v200 row_shr:1 row_mask:0xf bank_mask:0xf
	v_fmac_f32_dpp v237, v117, v201 row_shr:1 row_mask:0xf bank_mask:0xf
	v_fmac_f32_dpp v230, v118, v190 row_shl:1 row_mask:0xf bank_mask:0xf
	v_fmac_f32_dpp v231, v119, v191 row_shl:1 row_mask:0xf bank_mask:0xf
	v_fmac_f32_dpp v232, v120, v192 row_shl:1 row_mask:0xf bank_mask:0xf
	v_fmac_f32_dpp v233, v121, v193 row_shl:1 row_mask:0xf bank_mask:0xf
	v_fmac_f32_dpp v234, v114, v206 row_shl:1 row_mask:0xf bank_mask:0xf
	v_fmac_f32_dpp v235, v115, v207 row_shl:1 row_mask:0xf bank_mask:0xf
	v_fmac_f32_dpp v236, v116, v208 row_shl:1 row_mask:0xf bank_mask:0xf
	v_fmac_f32_dpp v237, v117, v209 row_shl:1 row_mask:0xf bank_mask:0xf
	v_fmac_f32_dpp v230, v126, v214 row_ror:1 row_mask:0xf bank_mask:0xf
	v_fmac_f32_dpp v231, v127, v215 row_ror:1 row_mask:0xf bank_mask:0xf
	v_fmac_f32_dpp v232, v128, v216 row_ror:1 row_mask:0xf bank_mask:0xf
	v_fmac_f32_dpp v233, v129, v217 row_ror:1 row_mask:0xf bank_mask:0xf
	v_fmac_f32_dpp v234, v122, v218 row_ror:1 row_mask:0xf bank_mask:0xf
	v_fmac_f32_dpp v235, v123, v219 row_ror:1 row_mask:0xf bank_mask:0xf
	v_fmac_f32_dpp v236, v124, v220 row_ror:1 row_mask:0xf bank_mask:0xf
	v_fmac_f32_dpp v237, v125, v221 row_ror:1 row_mask:0xf bank_mask:0xf
	v_fmac_f32_dpp v230, v110, v222 row_ror:15 row_mask:0xf bank_mask:0xf
	v_fmac_f32_dpp v231, v111, v223 row_ror:15 row_mask:0xf bank_mask:0xf
	v_fmac_f32_dpp v232, v112, v224 row_ror:15 row_mask:0xf bank_mask:0xf
	v_fmac_f32_dpp v233, v113, v225 row_ror:15 row_mask:0xf bank_mask:0xf
; __device__ __forceinline__ unsigned cvt_pk_bf16(float lo, float hi) { unsigned r; asm volatile("v_cvt_pk_bf16_f32 %0, %1, %2" : "=v"(r) : "v"(lo), "v"(hi)); return r; }
; __device__ __forceinline__ float sigmoid_f(float x) { return fast_rcp(1.0f + fast_exp2(-1.4426950409f * x)); }
;     __device__ __forceinline__ void operator()(f32x4 (&acc)[2][2][4][2], const Unit& u, int wr, int wc, int fr, int fq) const {
;     ...
;                         const f32x4 cur = acc[ai][bj][m][n], lo = acc[ai][bj][m > 0 ? m - 1 : 0][n], hi = acc[ai][bj][m < 3 ? m + 1 : 3][n];
;                         f32x4 pv, nv;
; #pragma unroll
;                         for (int idx = 0; idx < 4; ++idx) {
;                             const float y = (fr == 15) ? lo[idx] : cur[idx], z = (fr == 0) ? hi[idx] : cur[idx];
;                             pv[idx] = __int_as_float(__builtin_amdgcn_update_dpp(0, __float_as_int(y), 0x121, 0xf, 0xf, false));
;                             nv[idx] = __int_as_float(__builtin_amdgcn_update_dpp(0, __float_as_int(z), 0x12f, 0xf, 0xf, false));
;                         }
;                         cv[bj] = kc[bj][0] * pv + kc[bj][1] * cur + kc[bj][2] * nv + bc[bj];
;                     }
;                     const int row = row0 + ai * HALF + m * 16;
;                     const bool edge = (m == 0 && fr == 0) || (m == 3 && fr == 15);
;                     if (!edge) { const f32x4 gt = cv[0], vl = cv[1];
;                         u32x2 w; w.x = cvt_pk_bf16(gt[0] * sigmoid_f(gt[0]) * vl[0], gt[1] * sigmoid_f(gt[1]) * vl[1]); w.y = cvt_pk_bf16(gt[2] * sigmoid_f(gt[2]) * vl[2], gt[3] * sigmoid_f(gt[3]) * vl[3]);
;                         *(u32x2*)(ACT + (size_t)row * FF + j4) = w; }
	v_fmac_f32_dpp v234, v102, v226 row_ror:15 row_mask:0xf bank_mask:0xf
	v_fmac_f32_dpp v235, v103, v227 row_ror:15 row_mask:0xf bank_mask:0xf
	v_fmac_f32_dpp v236, v104, v228 row_ror:15 row_mask:0xf bank_mask:0xf
	v_fmac_f32_dpp v237, v105, v229 row_ror:15 row_mask:0xf bank_mask:0xf
	v_pk_mul_f32 v[174:175], v[230:231], s[34:35]
	v_pk_mul_f32 v[176:177], v[232:233], s[34:35]
	v_exp_f32_e32 v174, v174
	v_exp_f32_e32 v175, v175
	v_exp_f32_e32 v176, v176
	v_exp_f32_e32 v177, v177
	v_pk_add_f32 v[174:175], v[174:175], s[36:37]
	v_pk_add_f32 v[176:177], v[176:177], s[36:37]
	v_rcp_f32_e32 v174, v174
	v_rcp_f32_e32 v175, v175
	v_rcp_f32_e32 v176, v176
	v_rcp_f32_e32 v177, v177
	v_pk_mul_f32 v[174:175], v[230:231], v[174:175]
	v_pk_mul_f32 v[176:177], v[232:233], v[176:177]
	v_pk_mul_f32 v[174:175], v[174:175], v[234:235]
	v_pk_mul_f32 v[176:177], v[176:177], v[236:237]
	v_cvt_pk_bf16_f32 v180, v174, v175
	v_cvt_pk_bf16_f32 v181, v176, v177
	v_add_u32_e32 v239, 0x2b000, v238
	global_store_dwordx2 v239, v[180:181], s[30:31]
	v_pk_fma_f32 v[230:231], v[110:111], v[186:187], v[194:195]
	v_pk_fma_f32 v[232:233], v[112:113], v[188:189], v[196:197]
	v_pk_fma_f32 v[234:235], v[102:103], v[202:203], v[210:211]
	v_pk_fma_f32 v[236:237], v[104:105], v[204:205], v[212:213]
	v_fmac_f32_dpp v230, v110, v182 row_shr:1 row_mask:0xf bank_mask:0xf
	v_fmac_f32_dpp v231, v111, v183 row_shr:1 row_mask:0xf bank_mask:0xf
	v_fmac_f32_dpp v232, v112, v184 row_shr:1 row_mask:0xf bank_mask:0xf
	v_fmac_f32_dpp v233, v113, v185 row_shr:1 row_mask:0xf bank_mask:0xf
	v_fmac_f32_dpp v234, v102, v198 row_shr:1 row_mask:0xf bank_mask:0xf
	v_fmac_f32_dpp v235, v103, v199 row_shr:1 row_mask:0xf bank_mask:0xf
	v_fmac_f32_dpp v236, v104, v200 row_shr:1 row_mask:0xf bank_mask:0xf
	v_fmac_f32_dpp v237, v105, v201 row_shr:1 row_mask:0xf bank_mask:0xf
	v_fmac_f32_dpp v230, v110, v190 row_shl:1 row_mask:0xf bank_mask:0xf
	v_fmac_f32_dpp v231, v111, v191 row_shl:1 row_mask:0xf bank_mask:0xf
	v_fmac_f32_dpp v232, v112, v192 row_shl:1 row_mask:0xf bank_mask:0xf
	v_fmac_f32_dpp v233, v113, v193 row_shl:1 row_mask:0xf bank_mask:0xf
	v_fmac_f32_dpp v234, v102, v206 row_shl:1 row_mask:0xf bank_mask:0xf
	v_fmac_f32_dpp v235, v103, v207 row_shl:1 row_mask:0xf bank_mask:0xf
	v_fmac_f32_dpp v236, v104, v208 row_shl:1 row_mask:0xf bank_mask:0xf
	v_fmac_f32_dpp v237, v105, v209 row_shl:1 row_mask:0xf bank_mask:0xf
	v_fmac_f32_dpp v230, v118, v214 row_ror:1 row_mask:0xf bank_mask:0xf
	v_fmac_f32_dpp v231, v119, v215 row_ror:1 row_mask:0xf bank_mask:0xf
	v_fmac_f32_dpp v232, v120, v216 row_ror:1 row_mask:0xf bank_mask:0xf
	v_fmac_f32_dpp v233, v121, v217 row_ror:1 row_mask:0xf bank_mask:0xf
	v_fmac_f32_dpp v234, v114, v218 row_ror:1 row_mask:0xf bank_mask:0xf
	v_fmac_f32_dpp v235, v115, v219 row_ror:1 row_mask:0xf bank_mask:0xf
	v_fmac_f32_dpp v236, v116, v220 row_ror:1 row_mask:0xf bank_mask:0xf
	v_fmac_f32_dpp v237, v117, v221 row_ror:1 row_mask:0xf bank_mask:0xf
	v_fmac_f32_dpp v230, v106, v222 row_ror:15 row_mask:0xf bank_mask:0xf
	v_fmac_f32_dpp v231, v107, v223 row_ror:15 row_mask:0xf bank_mask:0xf
	v_fmac_f32_dpp v232, v108, v224 row_ror:15 row_mask:0xf bank_mask:0xf
	v_fmac_f32_dpp v233, v109, v225 row_ror:15 row_mask:0xf bank_mask:0xf
	v_fmac_f32_dpp v234, v98, v226 row_ror:15 row_mask:0xf bank_mask:0xf
	v_fmac_f32_dpp v235, v99, v227 row_ror:15 row_mask:0xf bank_mask:0xf
	v_fmac_f32_dpp v236, v100, v228 row_ror:15 row_mask:0xf bank_mask:0xf
	v_fmac_f32_dpp v237, v101, v229 row_ror:15 row_mask:0xf bank_mask:0xf
	v_pk_mul_f32 v[174:175], v[230:231], s[34:35]
	v_pk_mul_f32 v[176:177], v[232:233], s[34:35]
	v_exp_f32_e32 v174, v174
	v_exp_f32_e32 v175, v175
	v_exp_f32_e32 v176, v176
	v_exp_f32_e32 v177, v177
	v_pk_add_f32 v[174:175], v[174:175], s[36:37]
	v_pk_add_f32 v[176:177], v[176:177], s[36:37]
	v_rcp_f32_e32 v174, v174
	v_rcp_f32_e32 v175, v175
	v_rcp_f32_e32 v176, v176
	v_rcp_f32_e32 v177, v177
	v_pk_mul_f32 v[174:175], v[230:231], v[174:175]
	v_pk_mul_f32 v[176:177], v[232:233], v[176:177]
	v_pk_mul_f32 v[174:175], v[174:175], v[234:235]
	v_pk_mul_f32 v[176:177], v[176:177], v[236:237]
	v_cvt_pk_bf16_f32 v178, v174, v175
	v_cvt_pk_bf16_f32 v179, v176, v177
	v_add_u32_e32 v239, 0x56000, v238
	global_store_dwordx2 v239, v[178:179], s[30:31]
	v_pk_fma_f32 v[230:231], v[106:107], v[186:187], v[194:195]
	v_pk_fma_f32 v[232:233], v[108:109], v[188:189], v[196:197]
	v_pk_fma_f32 v[234:235], v[98:99], v[202:203], v[210:211]
	v_pk_fma_f32 v[236:237], v[100:101], v[204:205], v[212:213]
	v_fmac_f32_dpp v230, v106, v182 row_shr:1 row_mask:0xf bank_mask:0xf
	v_fmac_f32_dpp v231, v107, v183 row_shr:1 row_mask:0xf bank_mask:0xf
	v_fmac_f32_dpp v232, v108, v184 row_shr:1 row_mask:0xf bank_mask:0xf
	v_fmac_f32_dpp v233, v109, v185 row_shr:1 row_mask:0xf bank_mask:0xf
	v_fmac_f32_dpp v234, v98, v198 row_shr:1 row_mask:0xf bank_mask:0xf
	v_fmac_f32_dpp v235, v99, v199 row_shr:1 row_mask:0xf bank_mask:0xf
	v_fmac_f32_dpp v236, v100, v200 row_shr:1 row_mask:0xf bank_mask:0xf
	v_fmac_f32_dpp v237, v101, v201 row_shr:1 row_mask:0xf bank_mask:0xf
	v_fmac_f32_dpp v230, v106, v190 row_shl:1 row_mask:0xf bank_mask:0xf
	v_fmac_f32_dpp v231, v107, v191 row_shl:1 row_mask:0xf bank_mask:0xf
	v_fmac_f32_dpp v232, v108, v192 row_shl:1 row_mask:0xf bank_mask:0xf
	v_fmac_f32_dpp v233, v109, v193 row_shl:1 row_mask:0xf bank_mask:0xf
	v_fmac_f32_dpp v234, v98, v206 row_shl:1 row_mask:0xf bank_mask:0xf
	v_fmac_f32_dpp v235, v99, v207 row_shl:1 row_mask:0xf bank_mask:0xf
	v_fmac_f32_dpp v236, v100, v208 row_shl:1 row_mask:0xf bank_mask:0xf
	v_fmac_f32_dpp v237, v101, v209 row_shl:1 row_mask:0xf bank_mask:0xf
; __device__ __forceinline__ unsigned cvt_pk_bf16(float lo, float hi) { unsigned r; asm volatile("v_cvt_pk_bf16_f32 %0, %1, %2" : "=v"(r) : "v"(lo), "v"(hi)); return r; }
; __device__ __forceinline__ float sigmoid_f(float x) { return fast_rcp(1.0f + fast_exp2(-1.4426950409f * x)); }
;     __device__ __forceinline__ void operator()(f32x4 (&acc)[2][2][4][2], const Unit& u, int wr, int wc, int fr, int fq) const {
;     ...
;             for (int bj = 0; bj < 2; ++bj) { bc[bj] = *(const f32x4*)(cb + bj * FF + j4);
; #pragma unroll
;                 for (int w = 0; w < 3; ++w) kc[bj][w] = *(const f32x4*)(ck + w * NUP + bj * FF + j4); }
;     ...
;                         const f32x4 cur = acc[ai][bj][m][n], lo = acc[ai][bj][m > 0 ? m - 1 : 0][n], hi = acc[ai][bj][m < 3 ? m + 1 : 3][n];
;                         f32x4 pv, nv;
; #pragma unroll
;                         for (int idx = 0; idx < 4; ++idx) {
;                             const float y = (fr == 15) ? lo[idx] : cur[idx], z = (fr == 0) ? hi[idx] : cur[idx];
;                             pv[idx] = __int_as_float(__builtin_amdgcn_update_dpp(0, __float_as_int(y), 0x121, 0xf, 0xf, false));
;                             nv[idx] = __int_as_float(__builtin_amdgcn_update_dpp(0, __float_as_int(z), 0x12f, 0xf, 0xf, false));
;                         }
;                         cv[bj] = kc[bj][0] * pv + kc[bj][1] * cur + kc[bj][2] * nv + bc[bj];
;                     }
;                     const int row = row0 + ai * HALF + m * 16;
;                     const bool edge = (m == 0 && fr == 0) || (m == 3 && fr == 15);
;                     if (!edge) { const f32x4 gt = cv[0], vl = cv[1];
;                         u32x2 w; w.x = cvt_pk_bf16(gt[0] * sigmoid_f(gt[0]) * vl[0], gt[1] * sigmoid_f(gt[1]) * vl[1]); w.y = cvt_pk_bf16(gt[2] * sigmoid_f(gt[2]) * vl[2], gt[3] * sigmoid_f(gt[3]) * vl[3]);
;                         *(u32x2*)(ACT + (size_t)row * FF + j4) = w; }
	v_fmac_f32_dpp v230, v110, v214 row_ror:1 row_mask:0xf bank_mask:0xf
	v_fmac_f32_dpp v231, v111, v215 row_ror:1 row_mask:0xf bank_mask:0xf
	v_fmac_f32_dpp v232, v112, v216 row_ror:1 row_mask:0xf bank_mask:0xf
	v_fmac_f32_dpp v233, v113, v217 row_ror:1 row_mask:0xf bank_mask:0xf
	v_fmac_f32_dpp v234, v102, v218 row_ror:1 row_mask:0xf bank_mask:0xf
	v_fmac_f32_dpp v235, v103, v219 row_ror:1 row_mask:0xf bank_mask:0xf
	v_fmac_f32_dpp v236, v104, v220 row_ror:1 row_mask:0xf bank_mask:0xf
	v_fmac_f32_dpp v237, v105, v221 row_ror:1 row_mask:0xf bank_mask:0xf
	v_pk_mul_f32 v[174:175], v[230:231], s[34:35]
	v_pk_mul_f32 v[176:177], v[232:233], s[34:35]
	v_exp_f32_e32 v174, v174
	v_exp_f32_e32 v175, v175
	v_exp_f32_e32 v176, v176
	v_exp_f32_e32 v177, v177
	v_pk_add_f32 v[174:175], v[174:175], s[36:37]
	v_pk_add_f32 v[176:177], v[176:177], s[36:37]
	v_rcp_f32_e32 v174, v174
	v_rcp_f32_e32 v175, v175
	v_rcp_f32_e32 v176, v176
	v_rcp_f32_e32 v177, v177
	v_pk_mul_f32 v[174:175], v[230:231], v[174:175]
	v_pk_mul_f32 v[176:177], v[232:233], v[176:177]
	v_pk_mul_f32 v[174:175], v[174:175], v[234:235]
	v_pk_mul_f32 v[176:177], v[176:177], v[236:237]
	v_cvt_pk_bf16_f32 v180, v174, v175
	v_cvt_pk_bf16_f32 v181, v176, v177
	v_add_u32_e32 v239, 0x81000, v238
	s_and_saveexec_b64 s[16:17], s[40:41]
	global_store_dwordx2 v239, v[180:181], s[30:31]
	s_or_b64 exec, exec, s[16:17]
	global_load_dwordx4 v[126:129], v242, s[18:19] offset:16
	global_load_dwordx4 v[118:121], v133, s[18:19] offset:16
	global_load_dwordx4 v[110:113], v137, s[18:19] offset:16
	global_load_dwordx4 v[106:109], v242, s[20:21] offset:16
	global_load_dwordx4 v[122:125], v131, s[18:19] offset:16
	global_load_dwordx4 v[114:117], v135, s[18:19] offset:16
	global_load_dwordx4 v[102:105], v139, s[18:19] offset:16
	global_load_dwordx4 v[98:101], v131, s[20:21] offset:16
	v_pk_fma_f32 v[230:231], v[94:95], v[186:187], v[194:195]
	v_pk_fma_f32 v[232:233], v[96:97], v[188:189], v[196:197]
	v_pk_fma_f32 v[234:235], v[86:87], v[202:203], v[210:211]
	v_pk_fma_f32 v[236:237], v[88:89], v[204:205], v[212:213]
	v_fmac_f32_dpp v230, v94, v182 row_shr:1 row_mask:0xf bank_mask:0xf
	v_fmac_f32_dpp v231, v95, v183 row_shr:1 row_mask:0xf bank_mask:0xf
	v_fmac_f32_dpp v232, v96, v184 row_shr:1 row_mask:0xf bank_mask:0xf
	v_fmac_f32_dpp v233, v97, v185 row_shr:1 row_mask:0xf bank_mask:0xf
	v_fmac_f32_dpp v234, v86, v198 row_shr:1 row_mask:0xf bank_mask:0xf
	v_fmac_f32_dpp v235, v87, v199 row_shr:1 row_mask:0xf bank_mask:0xf
	v_fmac_f32_dpp v236, v88, v200 row_shr:1 row_mask:0xf bank_mask:0xf
	v_fmac_f32_dpp v237, v89, v201 row_shr:1 row_mask:0xf bank_mask:0xf
	v_fmac_f32_dpp v230, v94, v190 row_shl:1 row_mask:0xf bank_mask:0xf
	v_fmac_f32_dpp v231, v95, v191 row_shl:1 row_mask:0xf bank_mask:0xf
	v_fmac_f32_dpp v232, v96, v192 row_shl:1 row_mask:0xf bank_mask:0xf
	v_fmac_f32_dpp v233, v97, v193 row_shl:1 row_mask:0xf bank_mask:0xf
	v_fmac_f32_dpp v234, v86, v206 row_shl:1 row_mask:0xf bank_mask:0xf
	v_fmac_f32_dpp v235, v87, v207 row_shl:1 row_mask:0xf bank_mask:0xf
	v_fmac_f32_dpp v236, v88, v208 row_shl:1 row_mask:0xf bank_mask:0xf
	v_fmac_f32_dpp v237, v89, v209 row_shl:1 row_mask:0xf bank_mask:0xf
	v_fmac_f32_dpp v230, v90, v222 row_ror:15 row_mask:0xf bank_mask:0xf
	v_fmac_f32_dpp v231, v91, v223 row_ror:15 row_mask:0xf bank_mask:0xf
	v_fmac_f32_dpp v232, v92, v224 row_ror:15 row_mask:0xf bank_mask:0xf
	v_fmac_f32_dpp v233, v93, v225 row_ror:15 row_mask:0xf bank_mask:0xf
	v_fmac_f32_dpp v234, v82, v226 row_ror:15 row_mask:0xf bank_mask:0xf
	v_fmac_f32_dpp v235, v83, v227 row_ror:15 row_mask:0xf bank_mask:0xf
	v_fmac_f32_dpp v236, v84, v228 row_ror:15 row_mask:0xf bank_mask:0xf
	v_fmac_f32_dpp v237, v85, v229 row_ror:15 row_mask:0xf bank_mask:0xf
	v_pk_mul_f32 v[174:175], v[230:231], s[34:35]
	v_pk_mul_f32 v[176:177], v[232:233], s[34:35]
	v_exp_f32_e32 v174, v174
	v_exp_f32_e32 v175, v175
	v_exp_f32_e32 v176, v176
	v_exp_f32_e32 v177, v177
	v_pk_add_f32 v[174:175], v[174:175], s[36:37]
	v_pk_add_f32 v[176:177], v[176:177], s[36:37]
	v_rcp_f32_e32 v174, v174
	v_rcp_f32_e32 v175, v175
	v_rcp_f32_e32 v176, v176
	v_rcp_f32_e32 v177, v177
	v_pk_mul_f32 v[174:175], v[230:231], v[174:175]
	v_pk_mul_f32 v[176:177], v[232:233], v[176:177]
	v_pk_mul_f32 v[174:175], v[174:175], v[234:235]
	v_pk_mul_f32 v[176:177], v[176:177], v[236:237]
	v_cvt_pk_bf16_f32 v180, v174, v175
	v_cvt_pk_bf16_f32 v181, v176, v177
	v_add_u32_e32 v239, 0x158000, v238
	s_and_saveexec_b64 s[16:17], s[44:45]
	global_store_dwordx2 v239, v[180:181], s[30:31]
	s_or_b64 exec, exec, s[16:17]
	v_pk_fma_f32 v[230:231], v[90:91], v[186:187], v[194:195]
	v_pk_fma_f32 v[232:233], v[92:93], v[188:189], v[196:197]
	v_pk_fma_f32 v[234:235], v[82:83], v[202:203], v[210:211]
	v_pk_fma_f32 v[236:237], v[84:85], v[204:205], v[212:213]
	v_fmac_f32_dpp v230, v90, v182 row_shr:1 row_mask:0xf bank_mask:0xf
	v_fmac_f32_dpp v231, v91, v183 row_shr:1 row_mask:0xf bank_mask:0xf
	v_fmac_f32_dpp v232, v92, v184 row_shr:1 row_mask:0xf bank_mask:0xf
	v_fmac_f32_dpp v233, v93, v185 row_shr:1 row_mask:0xf bank_mask:0xf
	v_fmac_f32_dpp v234, v82, v198 row_shr:1 row_mask:0xf bank_mask:0xf
	v_fmac_f32_dpp v235, v83, v199 row_shr:1 row_mask:0xf bank_mask:0xf
	v_fmac_f32_dpp v236, v84, v200 row_shr:1 row_mask:0xf bank_mask:0xf
	v_fmac_f32_dpp v237, v85, v201 row_shr:1 row_mask:0xf bank_mask:0xf
	v_fmac_f32_dpp v230, v90, v190 row_shl:1 row_mask:0xf bank_mask:0xf
	v_fmac_f32_dpp v231, v91, v191 row_shl:1 row_mask:0xf bank_mask:0xf
	v_fmac_f32_dpp v232, v92, v192 row_shl:1 row_mask:0xf bank_mask:0xf
	v_fmac_f32_dpp v233, v93, v193 row_shl:1 row_mask:0xf bank_mask:0xf
; __device__ __forceinline__ unsigned cvt_pk_bf16(float lo, float hi) { unsigned r; asm volatile("v_cvt_pk_bf16_f32 %0, %1, %2" : "=v"(r) : "v"(lo), "v"(hi)); return r; }
; __device__ __forceinline__ float sigmoid_f(float x) { return fast_rcp(1.0f + fast_exp2(-1.4426950409f * x)); }
;     __device__ __forceinline__ void operator()(f32x4 (&acc)[2][2][4][2], const Unit& u, int wr, int wc, int fr, int fq) const {
;     ...
;                         const f32x4 cur = acc[ai][bj][m][n], lo = acc[ai][bj][m > 0 ? m - 1 : 0][n], hi = acc[ai][bj][m < 3 ? m + 1 : 3][n];
;                         f32x4 pv, nv;
; #pragma unroll
;                         for (int idx = 0; idx < 4; ++idx) {
;                             const float y = (fr == 15) ? lo[idx] : cur[idx], z = (fr == 0) ? hi[idx] : cur[idx];
;                             pv[idx] = __int_as_float(__builtin_amdgcn_update_dpp(0, __float_as_int(y), 0x121, 0xf, 0xf, false));
;                             nv[idx] = __int_as_float(__builtin_amdgcn_update_dpp(0, __float_as_int(z), 0x12f, 0xf, 0xf, false));
;                         }
;                         cv[bj] = kc[bj][0] * pv + kc[bj][1] * cur + kc[bj][2] * nv + bc[bj];
;                     }
;                     const int row = row0 + ai * HALF + m * 16;
;                     const bool edge = (m == 0 && fr == 0) || (m == 3 && fr == 15);
;                     if (!edge) { const f32x4 gt = cv[0], vl = cv[1];
;                         u32x2 w; w.x = cvt_pk_bf16(gt[0] * sigmoid_f(gt[0]) * vl[0], gt[1] * sigmoid_f(gt[1]) * vl[1]); w.y = cvt_pk_bf16(gt[2] * sigmoid_f(gt[2]) * vl[2], gt[3] * sigmoid_f(gt[3]) * vl[3]);
;                         *(u32x2*)(ACT + (size_t)row * FF + j4) = w; }
	v_fmac_f32_dpp v234, v82, v206 row_shl:1 row_mask:0xf bank_mask:0xf
	v_fmac_f32_dpp v235, v83, v207 row_shl:1 row_mask:0xf bank_mask:0xf
	v_fmac_f32_dpp v236, v84, v208 row_shl:1 row_mask:0xf bank_mask:0xf
	v_fmac_f32_dpp v237, v85, v209 row_shl:1 row_mask:0xf bank_mask:0xf
	v_fmac_f32_dpp v230, v94, v214 row_ror:1 row_mask:0xf bank_mask:0xf
	v_fmac_f32_dpp v231, v95, v215 row_ror:1 row_mask:0xf bank_mask:0xf
	v_fmac_f32_dpp v232, v96, v216 row_ror:1 row_mask:0xf bank_mask:0xf
	v_fmac_f32_dpp v233, v97, v217 row_ror:1 row_mask:0xf bank_mask:0xf
	v_fmac_f32_dpp v234, v86, v218 row_ror:1 row_mask:0xf bank_mask:0xf
	v_fmac_f32_dpp v235, v87, v219 row_ror:1 row_mask:0xf bank_mask:0xf
	v_fmac_f32_dpp v236, v88, v220 row_ror:1 row_mask:0xf bank_mask:0xf
	v_fmac_f32_dpp v237, v89, v221 row_ror:1 row_mask:0xf bank_mask:0xf
	v_fmac_f32_dpp v230, v78, v222 row_ror:15 row_mask:0xf bank_mask:0xf
	v_fmac_f32_dpp v231, v79, v223 row_ror:15 row_mask:0xf bank_mask:0xf
	v_fmac_f32_dpp v232, v80, v224 row_ror:15 row_mask:0xf bank_mask:0xf
	v_fmac_f32_dpp v233, v81, v225 row_ror:15 row_mask:0xf bank_mask:0xf
	v_fmac_f32_dpp v234, v70, v226 row_ror:15 row_mask:0xf bank_mask:0xf
	v_fmac_f32_dpp v235, v71, v227 row_ror:15 row_mask:0xf bank_mask:0xf
	v_fmac_f32_dpp v236, v72, v228 row_ror:15 row_mask:0xf bank_mask:0xf
	v_fmac_f32_dpp v237, v73, v229 row_ror:15 row_mask:0xf bank_mask:0xf
	v_pk_mul_f32 v[174:175], v[230:231], s[34:35]
	v_pk_mul_f32 v[176:177], v[232:233], s[34:35]
	v_exp_f32_e32 v174, v174
	v_exp_f32_e32 v175, v175
	v_exp_f32_e32 v176, v176
	v_exp_f32_e32 v177, v177
	v_pk_add_f32 v[174:175], v[174:175], s[36:37]
	v_pk_add_f32 v[176:177], v[176:177], s[36:37]
	v_rcp_f32_e32 v174, v174
	v_rcp_f32_e32 v175, v175
	v_rcp_f32_e32 v176, v176
	v_rcp_f32_e32 v177, v177
	v_pk_mul_f32 v[174:175], v[230:231], v[174:175]
	v_pk_mul_f32 v[176:177], v[232:233], v[176:177]
	v_pk_mul_f32 v[174:175], v[174:175], v[234:235]
	v_pk_mul_f32 v[176:177], v[176:177], v[236:237]
	v_cvt_pk_bf16_f32 v178, v174, v175
	v_cvt_pk_bf16_f32 v179, v176, v177
	v_add_u32_e32 v239, 0x183000, v238
	global_store_dwordx2 v239, v[178:179], s[30:31]
	v_pk_fma_f32 v[230:231], v[78:79], v[186:187], v[194:195]
	v_pk_fma_f32 v[232:233], v[80:81], v[188:189], v[196:197]
	v_pk_fma_f32 v[234:235], v[70:71], v[202:203], v[210:211]
	v_pk_fma_f32 v[236:237], v[72:73], v[204:205], v[212:213]
	v_fmac_f32_dpp v230, v78, v182 row_shr:1 row_mask:0xf bank_mask:0xf
	v_fmac_f32_dpp v231, v79, v183 row_shr:1 row_mask:0xf bank_mask:0xf
	v_fmac_f32_dpp v232, v80, v184 row_shr:1 row_mask:0xf bank_mask:0xf
	v_fmac_f32_dpp v233, v81, v185 row_shr:1 row_mask:0xf bank_mask:0xf
	v_fmac_f32_dpp v234, v70, v198 row_shr:1 row_mask:0xf bank_mask:0xf
	v_fmac_f32_dpp v235, v71, v199 row_shr:1 row_mask:0xf bank_mask:0xf
	v_fmac_f32_dpp v236, v72, v200 row_shr:1 row_mask:0xf bank_mask:0xf
	v_fmac_f32_dpp v237, v73, v201 row_shr:1 row_mask:0xf bank_mask:0xf
	v_fmac_f32_dpp v230, v78, v190 row_shl:1 row_mask:0xf bank_mask:0xf
	v_fmac_f32_dpp v231, v79, v191 row_shl:1 row_mask:0xf bank_mask:0xf
	v_fmac_f32_dpp v232, v80, v192 row_shl:1 row_mask:0xf bank_mask:0xf
	v_fmac_f32_dpp v233, v81, v193 row_shl:1 row_mask:0xf bank_mask:0xf
	v_fmac_f32_dpp v234, v70, v206 row_shl:1 row_mask:0xf bank_mask:0xf
	v_fmac_f32_dpp v235, v71, v207 row_shl:1 row_mask:0xf bank_mask:0xf
	v_fmac_f32_dpp v236, v72, v208 row_shl:1 row_mask:0xf bank_mask:0xf
	v_fmac_f32_dpp v237, v73, v209 row_shl:1 row_mask:0xf bank_mask:0xf
	v_fmac_f32_dpp v230, v90, v214 row_ror:1 row_mask:0xf bank_mask:0xf
	v_fmac_f32_dpp v231, v91, v215 row_ror:1 row_mask:0xf bank_mask:0xf
	v_fmac_f32_dpp v232, v92, v216 row_ror:1 row_mask:0xf bank_mask:0xf
	v_fmac_f32_dpp v233, v93, v217 row_ror:1 row_mask:0xf bank_mask:0xf
	v_fmac_f32_dpp v234, v82, v218 row_ror:1 row_mask:0xf bank_mask:0xf
	v_fmac_f32_dpp v235, v83, v219 row_ror:1 row_mask:0xf bank_mask:0xf
	v_fmac_f32_dpp v236, v84, v220 row_ror:1 row_mask:0xf bank_mask:0xf
	v_fmac_f32_dpp v237, v85, v221 row_ror:1 row_mask:0xf bank_mask:0xf
	v_fmac_f32_dpp v230, v74, v222 row_ror:15 row_mask:0xf bank_mask:0xf
	v_fmac_f32_dpp v231, v75, v223 row_ror:15 row_mask:0xf bank_mask:0xf
	v_fmac_f32_dpp v232, v76, v224 row_ror:15 row_mask:0xf bank_mask:0xf
	v_fmac_f32_dpp v233, v77, v225 row_ror:15 row_mask:0xf bank_mask:0xf
	v_fmac_f32_dpp v234, v66, v226 row_ror:15 row_mask:0xf bank_mask:0xf
	v_fmac_f32_dpp v235, v67, v227 row_ror:15 row_mask:0xf bank_mask:0xf
	v_fmac_f32_dpp v236, v68, v228 row_ror:15 row_mask:0xf bank_mask:0xf
	v_fmac_f32_dpp v237, v69, v229 row_ror:15 row_mask:0xf bank_mask:0xf
	v_pk_mul_f32 v[174:175], v[230:231], s[34:35]
	v_pk_mul_f32 v[176:177], v[232:233], s[34:35]
	v_exp_f32_e32 v174, v174
	v_exp_f32_e32 v175, v175
	v_exp_f32_e32 v176, v176
	v_exp_f32_e32 v177, v177
	v_pk_add_f32 v[174:175], v[174:175], s[36:37]
	v_pk_add_f32 v[176:177], v[176:177], s[36:37]
	v_rcp_f32_e32 v174, v174
	v_rcp_f32_e32 v175, v175
	v_rcp_f32_e32 v176, v176
	v_rcp_f32_e32 v177, v177
	v_pk_mul_f32 v[174:175], v[230:231], v[174:175]
	v_pk_mul_f32 v[176:177], v[232:233], v[176:177]
	v_pk_mul_f32 v[174:175], v[174:175], v[234:235]
	v_pk_mul_f32 v[176:177], v[176:177], v[236:237]
	v_cvt_pk_bf16_f32 v180, v174, v175
	v_cvt_pk_bf16_f32 v181, v176, v177
	v_add_u32_e32 v239, 0x1ae000, v238
	global_store_dwordx2 v239, v[180:181], s[30:31]
	v_pk_fma_f32 v[230:231], v[74:75], v[186:187], v[194:195]
	v_pk_fma_f32 v[232:233], v[76:77], v[188:189], v[196:197]
	v_pk_fma_f32 v[234:235], v[66:67], v[202:203], v[210:211]
	v_pk_fma_f32 v[236:237], v[68:69], v[204:205], v[212:213]
	v_fmac_f32_dpp v230, v74, v182 row_shr:1 row_mask:0xf bank_mask:0xf
; __device__ __forceinline__ unsigned cvt_pk_bf16(float lo, float hi) { unsigned r; asm volatile("v_cvt_pk_bf16_f32 %0, %1, %2" : "=v"(r) : "v"(lo), "v"(hi)); return r; }
; __device__ __forceinline__ float sigmoid_f(float x) { return fast_rcp(1.0f + fast_exp2(-1.4426950409f * x)); }
;     __device__ __forceinline__ void operator()(f32x4 (&acc)[2][2][4][2], const Unit& u, int wr, int wc, int fr, int fq) const {
;     ...
;                 for (int m = 0; m < 4; ++m) {
;                     f32x4 cv[2];
; #pragma unroll
;                     for (int bj = 0; bj < 2; ++bj) {
;                         const f32x4 cur = acc[ai][bj][m][n], lo = acc[ai][bj][m > 0 ? m - 1 : 0][n], hi = acc[ai][bj][m < 3 ? m + 1 : 3][n];
;                         f32x4 pv, nv;
; #pragma unroll
;                         for (int idx = 0; idx < 4; ++idx) {
;                             const float y = (fr == 15) ? lo[idx] : cur[idx], z = (fr == 0) ? hi[idx] : cur[idx];
;                             pv[idx] = __int_as_float(__builtin_amdgcn_update_dpp(0, __float_as_int(y), 0x121, 0xf, 0xf, false));
;                             nv[idx] = __int_as_float(__builtin_amdgcn_update_dpp(0, __float_as_int(z), 0x12f, 0xf, 0xf, false));
;                         }
;                         cv[bj] = kc[bj][0] * pv + kc[bj][1] * cur + kc[bj][2] * nv + bc[bj];
;                     }
;                     const int row = row0 + ai * HALF + m * 16;
;                     const bool edge = (m == 0 && fr == 0) || (m == 3 && fr == 15);
;                     if (!edge) { const f32x4 gt = cv[0], vl = cv[1];
;                         u32x2 w; w.x = cvt_pk_bf16(gt[0] * sigmoid_f(gt[0]) * vl[0], gt[1] * sigmoid_f(gt[1]) * vl[1]); w.y = cvt_pk_bf16(gt[2] * sigmoid_f(gt[2]) * vl[2], gt[3] * sigmoid_f(gt[3]) * vl[3]);
;                         *(u32x2*)(ACT + (size_t)row * FF + j4) = w; }
	v_fmac_f32_dpp v231, v75, v183 row_shr:1 row_mask:0xf bank_mask:0xf
	v_fmac_f32_dpp v232, v76, v184 row_shr:1 row_mask:0xf bank_mask:0xf
	v_fmac_f32_dpp v233, v77, v185 row_shr:1 row_mask:0xf bank_mask:0xf
	v_fmac_f32_dpp v234, v66, v198 row_shr:1 row_mask:0xf bank_mask:0xf
	v_fmac_f32_dpp v235, v67, v199 row_shr:1 row_mask:0xf bank_mask:0xf
	v_fmac_f32_dpp v236, v68, v200 row_shr:1 row_mask:0xf bank_mask:0xf
	v_fmac_f32_dpp v237, v69, v201 row_shr:1 row_mask:0xf bank_mask:0xf
	v_fmac_f32_dpp v230, v74, v190 row_shl:1 row_mask:0xf bank_mask:0xf
	v_fmac_f32_dpp v231, v75, v191 row_shl:1 row_mask:0xf bank_mask:0xf
	v_fmac_f32_dpp v232, v76, v192 row_shl:1 row_mask:0xf bank_mask:0xf
	v_fmac_f32_dpp v233, v77, v193 row_shl:1 row_mask:0xf bank_mask:0xf
	v_fmac_f32_dpp v234, v66, v206 row_shl:1 row_mask:0xf bank_mask:0xf
	v_fmac_f32_dpp v235, v67, v207 row_shl:1 row_mask:0xf bank_mask:0xf
	v_fmac_f32_dpp v236, v68, v208 row_shl:1 row_mask:0xf bank_mask:0xf
	v_fmac_f32_dpp v237, v69, v209 row_shl:1 row_mask:0xf bank_mask:0xf
	v_fmac_f32_dpp v230, v78, v214 row_ror:1 row_mask:0xf bank_mask:0xf
	v_fmac_f32_dpp v231, v79, v215 row_ror:1 row_mask:0xf bank_mask:0xf
	v_fmac_f32_dpp v232, v80, v216 row_ror:1 row_mask:0xf bank_mask:0xf
	v_fmac_f32_dpp v233, v81, v217 row_ror:1 row_mask:0xf bank_mask:0xf
	v_fmac_f32_dpp v234, v70, v218 row_ror:1 row_mask:0xf bank_mask:0xf
	v_fmac_f32_dpp v235, v71, v219 row_ror:1 row_mask:0xf bank_mask:0xf
	v_fmac_f32_dpp v236, v72, v220 row_ror:1 row_mask:0xf bank_mask:0xf
	v_fmac_f32_dpp v237, v73, v221 row_ror:1 row_mask:0xf bank_mask:0xf
	v_pk_mul_f32 v[174:175], v[230:231], s[34:35]
	v_pk_mul_f32 v[176:177], v[232:233], s[34:35]
	v_exp_f32_e32 v174, v174
	v_exp_f32_e32 v175, v175
	v_exp_f32_e32 v176, v176
	v_exp_f32_e32 v177, v177
	v_pk_add_f32 v[174:175], v[174:175], s[36:37]
	v_pk_add_f32 v[176:177], v[176:177], s[36:37]
	v_rcp_f32_e32 v174, v174
	v_rcp_f32_e32 v175, v175
	v_rcp_f32_e32 v176, v176
	v_rcp_f32_e32 v177, v177
	v_pk_mul_f32 v[174:175], v[230:231], v[174:175]
	v_pk_mul_f32 v[176:177], v[232:233], v[176:177]
	v_pk_mul_f32 v[174:175], v[174:175], v[234:235]
	v_pk_mul_f32 v[176:177], v[176:177], v[236:237]
	v_cvt_pk_bf16_f32 v178, v174, v175
	v_cvt_pk_bf16_f32 v179, v176, v177
	v_add_u32_e32 v239, 0x1d9000, v238
	s_and_saveexec_b64 s[16:17], s[40:41]
	global_store_dwordx2 v239, v[178:179], s[30:31]
	s_or_b64 exec, exec, s[16:17]
	s_waitcnt vmcnt(4)
	v_cndmask_b32_e64 v214, 0, v126, s[42:43]
	v_cndmask_b32_e64 v215, 0, v127, s[42:43]
	v_cndmask_b32_e64 v216, 0, v128, s[42:43]
	v_cndmask_b32_e64 v217, 0, v129, s[42:43]
	v_cndmask_b32_e64 v218, 0, v122, s[42:43]
	v_cndmask_b32_e64 v219, 0, v123, s[42:43]
	v_cndmask_b32_e64 v220, 0, v124, s[42:43]
	v_cndmask_b32_e64 v221, 0, v125, s[42:43]
	v_cndmask_b32_e64 v222, 0, v110, s[38:39]
	v_cndmask_b32_e64 v223, 0, v111, s[38:39]
	v_cndmask_b32_e64 v224, 0, v112, s[38:39]
	v_cndmask_b32_e64 v225, 0, v113, s[38:39]
	v_cndmask_b32_e64 v226, 0, v102, s[38:39]
	v_cndmask_b32_e64 v227, 0, v103, s[38:39]
	v_cndmask_b32_e64 v228, 0, v104, s[38:39]
	v_cndmask_b32_e64 v229, 0, v105, s[38:39]
	v_pk_fma_f32 v[230:231], v[62:63], v[118:119], v[106:107]
	v_pk_fma_f32 v[232:233], v[64:65], v[120:121], v[108:109]
	v_pk_fma_f32 v[234:235], v[54:55], v[114:115], v[98:99]
	v_pk_fma_f32 v[236:237], v[56:57], v[116:117], v[100:101]
	v_fmac_f32_dpp v230, v62, v126 row_shr:1 row_mask:0xf bank_mask:0xf
	v_fmac_f32_dpp v231, v63, v127 row_shr:1 row_mask:0xf bank_mask:0xf
	v_fmac_f32_dpp v232, v64, v128 row_shr:1 row_mask:0xf bank_mask:0xf
	v_fmac_f32_dpp v233, v65, v129 row_shr:1 row_mask:0xf bank_mask:0xf
	v_fmac_f32_dpp v234, v54, v122 row_shr:1 row_mask:0xf bank_mask:0xf
	v_fmac_f32_dpp v235, v55, v123 row_shr:1 row_mask:0xf bank_mask:0xf
	v_fmac_f32_dpp v236, v56, v124 row_shr:1 row_mask:0xf bank_mask:0xf
	v_fmac_f32_dpp v237, v57, v125 row_shr:1 row_mask:0xf bank_mask:0xf
	v_fmac_f32_dpp v230, v62, v110 row_shl:1 row_mask:0xf bank_mask:0xf
	v_fmac_f32_dpp v231, v63, v111 row_shl:1 row_mask:0xf bank_mask:0xf
	v_fmac_f32_dpp v232, v64, v112 row_shl:1 row_mask:0xf bank_mask:0xf
	v_fmac_f32_dpp v233, v65, v113 row_shl:1 row_mask:0xf bank_mask:0xf
	v_fmac_f32_dpp v234, v54, v102 row_shl:1 row_mask:0xf bank_mask:0xf
	v_fmac_f32_dpp v235, v55, v103 row_shl:1 row_mask:0xf bank_mask:0xf
	v_fmac_f32_dpp v236, v56, v104 row_shl:1 row_mask:0xf bank_mask:0xf
	v_fmac_f32_dpp v237, v57, v105 row_shl:1 row_mask:0xf bank_mask:0xf
	v_fmac_f32_dpp v230, v58, v222 row_ror:15 row_mask:0xf bank_mask:0xf
	v_fmac_f32_dpp v231, v59, v223 row_ror:15 row_mask:0xf bank_mask:0xf
	v_fmac_f32_dpp v232, v60, v224 row_ror:15 row_mask:0xf bank_mask:0xf
	v_fmac_f32_dpp v233, v61, v225 row_ror:15 row_mask:0xf bank_mask:0xf
	v_fmac_f32_dpp v234, v50, v226 row_ror:15 row_mask:0xf bank_mask:0xf
	v_fmac_f32_dpp v235, v51, v227 row_ror:15 row_mask:0xf bank_mask:0xf
	v_fmac_f32_dpp v236, v52, v228 row_ror:15 row_mask:0xf bank_mask:0xf
	v_fmac_f32_dpp v237, v53, v229 row_ror:15 row_mask:0xf bank_mask:0xf
	v_pk_mul_f32 v[174:175], v[230:231], s[34:35]
	v_pk_mul_f32 v[176:177], v[232:233], s[34:35]
	v_exp_f32_e32 v174, v174
	v_exp_f32_e32 v175, v175
	v_exp_f32_e32 v176, v176
	v_exp_f32_e32 v177, v177
	v_pk_add_f32 v[174:175], v[174:175], s[36:37]
	v_pk_add_f32 v[176:177], v[176:177], s[36:37]
	v_rcp_f32_e32 v174, v174
	v_rcp_f32_e32 v175, v175
	v_rcp_f32_e32 v176, v176
	v_rcp_f32_e32 v177, v177
	v_pk_mul_f32 v[174:175], v[230:231], v[174:175]
	v_pk_mul_f32 v[176:177], v[232:233], v[176:177]
	v_pk_mul_f32 v[174:175], v[174:175], v[234:235]
	v_pk_mul_f32 v[176:177], v[176:177], v[236:237]
	v_cvt_pk_bf16_f32 v178, v174, v175
; __device__ __forceinline__ unsigned cvt_pk_bf16(float lo, float hi) { unsigned r; asm volatile("v_cvt_pk_bf16_f32 %0, %1, %2" : "=v"(r) : "v"(lo), "v"(hi)); return r; }
; __device__ __forceinline__ float sigmoid_f(float x) { return fast_rcp(1.0f + fast_exp2(-1.4426950409f * x)); }
;     __device__ __forceinline__ void operator()(f32x4 (&acc)[2][2][4][2], const Unit& u, int wr, int wc, int fr, int fq) const {
;     ...
;                 for (int m = 0; m < 4; ++m) {
;                     f32x4 cv[2];
; #pragma unroll
;                     for (int bj = 0; bj < 2; ++bj) {
;                         const f32x4 cur = acc[ai][bj][m][n], lo = acc[ai][bj][m > 0 ? m - 1 : 0][n], hi = acc[ai][bj][m < 3 ? m + 1 : 3][n];
;                         f32x4 pv, nv;
; #pragma unroll
;                         for (int idx = 0; idx < 4; ++idx) {
;                             const float y = (fr == 15) ? lo[idx] : cur[idx], z = (fr == 0) ? hi[idx] : cur[idx];
;                             pv[idx] = __int_as_float(__builtin_amdgcn_update_dpp(0, __float_as_int(y), 0x121, 0xf, 0xf, false));
;                             nv[idx] = __int_as_float(__builtin_amdgcn_update_dpp(0, __float_as_int(z), 0x12f, 0xf, 0xf, false));
;                         }
;                         cv[bj] = kc[bj][0] * pv + kc[bj][1] * cur + kc[bj][2] * nv + bc[bj];
;                     }
;                     const int row = row0 + ai * HALF + m * 16;
;                     const bool edge = (m == 0 && fr == 0) || (m == 3 && fr == 15);
;                     if (!edge) { const f32x4 gt = cv[0], vl = cv[1];
;                         u32x2 w; w.x = cvt_pk_bf16(gt[0] * sigmoid_f(gt[0]) * vl[0], gt[1] * sigmoid_f(gt[1]) * vl[1]); w.y = cvt_pk_bf16(gt[2] * sigmoid_f(gt[2]) * vl[2], gt[3] * sigmoid_f(gt[3]) * vl[3]);
;                         *(u32x2*)(ACT + (size_t)row * FF + j4) = w; }
	v_cvt_pk_bf16_f32 v179, v176, v177
	s_and_saveexec_b64 s[16:17], s[44:45]
	global_store_dwordx2 v238, v[178:179], s[30:31] offset:8
	s_or_b64 exec, exec, s[16:17]
	v_pk_fma_f32 v[230:231], v[58:59], v[118:119], v[106:107]
	v_pk_fma_f32 v[232:233], v[60:61], v[120:121], v[108:109]
	v_pk_fma_f32 v[234:235], v[50:51], v[114:115], v[98:99]
	v_pk_fma_f32 v[236:237], v[52:53], v[116:117], v[100:101]
	v_fmac_f32_dpp v230, v58, v126 row_shr:1 row_mask:0xf bank_mask:0xf
	v_fmac_f32_dpp v231, v59, v127 row_shr:1 row_mask:0xf bank_mask:0xf
	v_fmac_f32_dpp v232, v60, v128 row_shr:1 row_mask:0xf bank_mask:0xf
	v_fmac_f32_dpp v233, v61, v129 row_shr:1 row_mask:0xf bank_mask:0xf
	v_fmac_f32_dpp v234, v50, v122 row_shr:1 row_mask:0xf bank_mask:0xf
	v_fmac_f32_dpp v235, v51, v123 row_shr:1 row_mask:0xf bank_mask:0xf
	v_fmac_f32_dpp v236, v52, v124 row_shr:1 row_mask:0xf bank_mask:0xf
	v_fmac_f32_dpp v237, v53, v125 row_shr:1 row_mask:0xf bank_mask:0xf
	v_fmac_f32_dpp v230, v58, v110 row_shl:1 row_mask:0xf bank_mask:0xf
	v_fmac_f32_dpp v231, v59, v111 row_shl:1 row_mask:0xf bank_mask:0xf
	v_fmac_f32_dpp v232, v60, v112 row_shl:1 row_mask:0xf bank_mask:0xf
	v_fmac_f32_dpp v233, v61, v113 row_shl:1 row_mask:0xf bank_mask:0xf
	v_fmac_f32_dpp v234, v50, v102 row_shl:1 row_mask:0xf bank_mask:0xf
	v_fmac_f32_dpp v235, v51, v103 row_shl:1 row_mask:0xf bank_mask:0xf
	v_fmac_f32_dpp v236, v52, v104 row_shl:1 row_mask:0xf bank_mask:0xf
	v_fmac_f32_dpp v237, v53, v105 row_shl:1 row_mask:0xf bank_mask:0xf
	v_fmac_f32_dpp v230, v62, v214 row_ror:1 row_mask:0xf bank_mask:0xf
	v_fmac_f32_dpp v231, v63, v215 row_ror:1 row_mask:0xf bank_mask:0xf
	v_fmac_f32_dpp v232, v64, v216 row_ror:1 row_mask:0xf bank_mask:0xf
	v_fmac_f32_dpp v233, v65, v217 row_ror:1 row_mask:0xf bank_mask:0xf
	v_fmac_f32_dpp v234, v54, v218 row_ror:1 row_mask:0xf bank_mask:0xf
	v_fmac_f32_dpp v235, v55, v219 row_ror:1 row_mask:0xf bank_mask:0xf
	v_fmac_f32_dpp v236, v56, v220 row_ror:1 row_mask:0xf bank_mask:0xf
	v_fmac_f32_dpp v237, v57, v221 row_ror:1 row_mask:0xf bank_mask:0xf
	v_fmac_f32_dpp v230, v46, v222 row_ror:15 row_mask:0xf bank_mask:0xf
	v_fmac_f32_dpp v231, v47, v223 row_ror:15 row_mask:0xf bank_mask:0xf
	v_fmac_f32_dpp v232, v48, v224 row_ror:15 row_mask:0xf bank_mask:0xf
	v_fmac_f32_dpp v233, v49, v225 row_ror:15 row_mask:0xf bank_mask:0xf
	v_fmac_f32_dpp v234, v38, v226 row_ror:15 row_mask:0xf bank_mask:0xf
	v_fmac_f32_dpp v235, v39, v227 row_ror:15 row_mask:0xf bank_mask:0xf
	v_fmac_f32_dpp v236, v40, v228 row_ror:15 row_mask:0xf bank_mask:0xf
	v_fmac_f32_dpp v237, v41, v229 row_ror:15 row_mask:0xf bank_mask:0xf
	v_pk_mul_f32 v[174:175], v[230:231], s[34:35]
	v_pk_mul_f32 v[176:177], v[232:233], s[34:35]
	v_exp_f32_e32 v174, v174
	v_exp_f32_e32 v175, v175
	v_exp_f32_e32 v176, v176
	v_exp_f32_e32 v177, v177
	v_pk_add_f32 v[174:175], v[174:175], s[36:37]
	v_pk_add_f32 v[176:177], v[176:177], s[36:37]
	v_rcp_f32_e32 v174, v174
	v_rcp_f32_e32 v175, v175
	v_rcp_f32_e32 v176, v176
	v_rcp_f32_e32 v177, v177
	v_pk_mul_f32 v[174:175], v[230:231], v[174:175]
	v_pk_mul_f32 v[176:177], v[232:233], v[176:177]
	v_pk_mul_f32 v[174:175], v[174:175], v[234:235]
	v_pk_mul_f32 v[176:177], v[176:177], v[236:237]
	v_cvt_pk_bf16_f32 v180, v174, v175
	v_cvt_pk_bf16_f32 v181, v176, v177
	v_add_u32_e32 v239, 0x2b000, v238
	global_store_dwordx2 v239, v[180:181], s[30:31] offset:8
	v_pk_fma_f32 v[230:231], v[46:47], v[118:119], v[106:107]
	v_pk_fma_f32 v[232:233], v[48:49], v[120:121], v[108:109]
	v_pk_fma_f32 v[234:235], v[38:39], v[114:115], v[98:99]
	v_pk_fma_f32 v[236:237], v[40:41], v[116:117], v[100:101]
	v_fmac_f32_dpp v230, v46, v126 row_shr:1 row_mask:0xf bank_mask:0xf
	v_fmac_f32_dpp v231, v47, v127 row_shr:1 row_mask:0xf bank_mask:0xf
	v_fmac_f32_dpp v232, v48, v128 row_shr:1 row_mask:0xf bank_mask:0xf
	v_fmac_f32_dpp v233, v49, v129 row_shr:1 row_mask:0xf bank_mask:0xf
	v_fmac_f32_dpp v234, v38, v122 row_shr:1 row_mask:0xf bank_mask:0xf
	v_fmac_f32_dpp v235, v39, v123 row_shr:1 row_mask:0xf bank_mask:0xf
	v_fmac_f32_dpp v236, v40, v124 row_shr:1 row_mask:0xf bank_mask:0xf
	v_fmac_f32_dpp v237, v41, v125 row_shr:1 row_mask:0xf bank_mask:0xf
	v_fmac_f32_dpp v230, v46, v110 row_shl:1 row_mask:0xf bank_mask:0xf
	v_fmac_f32_dpp v231, v47, v111 row_shl:1 row_mask:0xf bank_mask:0xf
	v_fmac_f32_dpp v232, v48, v112 row_shl:1 row_mask:0xf bank_mask:0xf
	v_fmac_f32_dpp v233, v49, v113 row_shl:1 row_mask:0xf bank_mask:0xf
	v_fmac_f32_dpp v234, v38, v102 row_shl:1 row_mask:0xf bank_mask:0xf
	v_fmac_f32_dpp v235, v39, v103 row_shl:1 row_mask:0xf bank_mask:0xf
	v_fmac_f32_dpp v236, v40, v104 row_shl:1 row_mask:0xf bank_mask:0xf
	v_fmac_f32_dpp v237, v41, v105 row_shl:1 row_mask:0xf bank_mask:0xf
	v_fmac_f32_dpp v230, v58, v214 row_ror:1 row_mask:0xf bank_mask:0xf
	v_fmac_f32_dpp v231, v59, v215 row_ror:1 row_mask:0xf bank_mask:0xf
	v_fmac_f32_dpp v232, v60, v216 row_ror:1 row_mask:0xf bank_mask:0xf
	v_fmac_f32_dpp v233, v61, v217 row_ror:1 row_mask:0xf bank_mask:0xf
	v_fmac_f32_dpp v234, v50, v218 row_ror:1 row_mask:0xf bank_mask:0xf
	v_fmac_f32_dpp v235, v51, v219 row_ror:1 row_mask:0xf bank_mask:0xf
	v_fmac_f32_dpp v236, v52, v220 row_ror:1 row_mask:0xf bank_mask:0xf
	v_fmac_f32_dpp v237, v53, v221 row_ror:1 row_mask:0xf bank_mask:0xf
	v_fmac_f32_dpp v230, v42, v222 row_ror:15 row_mask:0xf bank_mask:0xf
	v_fmac_f32_dpp v231, v43, v223 row_ror:15 row_mask:0xf bank_mask:0xf
	v_fmac_f32_dpp v232, v44, v224 row_ror:15 row_mask:0xf bank_mask:0xf
	v_fmac_f32_dpp v233, v45, v225 row_ror:15 row_mask:0xf bank_mask:0xf
	v_fmac_f32_dpp v234, v34, v226 row_ror:15 row_mask:0xf bank_mask:0xf
; __device__ __forceinline__ unsigned cvt_pk_bf16(float lo, float hi) { unsigned r; asm volatile("v_cvt_pk_bf16_f32 %0, %1, %2" : "=v"(r) : "v"(lo), "v"(hi)); return r; }
; __device__ __forceinline__ float sigmoid_f(float x) { return fast_rcp(1.0f + fast_exp2(-1.4426950409f * x)); }
;     __device__ __forceinline__ void operator()(f32x4 (&acc)[2][2][4][2], const Unit& u, int wr, int wc, int fr, int fq) const {
;     ...
;                 for (int m = 0; m < 4; ++m) {
;                     f32x4 cv[2];
; #pragma unroll
;                     for (int bj = 0; bj < 2; ++bj) {
;                         const f32x4 cur = acc[ai][bj][m][n], lo = acc[ai][bj][m > 0 ? m - 1 : 0][n], hi = acc[ai][bj][m < 3 ? m + 1 : 3][n];
;                         f32x4 pv, nv;
; #pragma unroll
;                         for (int idx = 0; idx < 4; ++idx) {
;                             const float y = (fr == 15) ? lo[idx] : cur[idx], z = (fr == 0) ? hi[idx] : cur[idx];
;                             pv[idx] = __int_as_float(__builtin_amdgcn_update_dpp(0, __float_as_int(y), 0x121, 0xf, 0xf, false));
;                             nv[idx] = __int_as_float(__builtin_amdgcn_update_dpp(0, __float_as_int(z), 0x12f, 0xf, 0xf, false));
;                         }
;                         cv[bj] = kc[bj][0] * pv + kc[bj][1] * cur + kc[bj][2] * nv + bc[bj];
;                     }
;                     const int row = row0 + ai * HALF + m * 16;
;                     const bool edge = (m == 0 && fr == 0) || (m == 3 && fr == 15);
;                     if (!edge) { const f32x4 gt = cv[0], vl = cv[1];
;                         u32x2 w; w.x = cvt_pk_bf16(gt[0] * sigmoid_f(gt[0]) * vl[0], gt[1] * sigmoid_f(gt[1]) * vl[1]); w.y = cvt_pk_bf16(gt[2] * sigmoid_f(gt[2]) * vl[2], gt[3] * sigmoid_f(gt[3]) * vl[3]);
;                         *(u32x2*)(ACT + (size_t)row * FF + j4) = w; }
	v_fmac_f32_dpp v235, v35, v227 row_ror:15 row_mask:0xf bank_mask:0xf
	v_fmac_f32_dpp v236, v36, v228 row_ror:15 row_mask:0xf bank_mask:0xf
	v_fmac_f32_dpp v237, v37, v229 row_ror:15 row_mask:0xf bank_mask:0xf
	v_pk_mul_f32 v[174:175], v[230:231], s[34:35]
	v_pk_mul_f32 v[176:177], v[232:233], s[34:35]
	v_exp_f32_e32 v174, v174
	v_exp_f32_e32 v175, v175
	v_exp_f32_e32 v176, v176
	v_exp_f32_e32 v177, v177
	v_pk_add_f32 v[174:175], v[174:175], s[36:37]
	v_pk_add_f32 v[176:177], v[176:177], s[36:37]
	v_rcp_f32_e32 v174, v174
	v_rcp_f32_e32 v175, v175
	v_rcp_f32_e32 v176, v176
	v_rcp_f32_e32 v177, v177
	v_pk_mul_f32 v[174:175], v[230:231], v[174:175]
	v_pk_mul_f32 v[176:177], v[232:233], v[176:177]
	v_pk_mul_f32 v[174:175], v[174:175], v[234:235]
	v_pk_mul_f32 v[176:177], v[176:177], v[236:237]
	v_cvt_pk_bf16_f32 v178, v174, v175
	v_cvt_pk_bf16_f32 v179, v176, v177
	v_add_u32_e32 v239, 0x56000, v238
	global_store_dwordx2 v239, v[178:179], s[30:31] offset:8
	v_pk_fma_f32 v[230:231], v[42:43], v[118:119], v[106:107]
	v_pk_fma_f32 v[232:233], v[44:45], v[120:121], v[108:109]
	v_pk_fma_f32 v[234:235], v[34:35], v[114:115], v[98:99]
	v_pk_fma_f32 v[236:237], v[36:37], v[116:117], v[100:101]
	v_fmac_f32_dpp v230, v42, v126 row_shr:1 row_mask:0xf bank_mask:0xf
	v_fmac_f32_dpp v231, v43, v127 row_shr:1 row_mask:0xf bank_mask:0xf
	v_fmac_f32_dpp v232, v44, v128 row_shr:1 row_mask:0xf bank_mask:0xf
	v_fmac_f32_dpp v233, v45, v129 row_shr:1 row_mask:0xf bank_mask:0xf
	v_fmac_f32_dpp v234, v34, v122 row_shr:1 row_mask:0xf bank_mask:0xf
	v_fmac_f32_dpp v235, v35, v123 row_shr:1 row_mask:0xf bank_mask:0xf
	v_fmac_f32_dpp v236, v36, v124 row_shr:1 row_mask:0xf bank_mask:0xf
	v_fmac_f32_dpp v237, v37, v125 row_shr:1 row_mask:0xf bank_mask:0xf
	v_fmac_f32_dpp v230, v42, v110 row_shl:1 row_mask:0xf bank_mask:0xf
	v_fmac_f32_dpp v231, v43, v111 row_shl:1 row_mask:0xf bank_mask:0xf
	v_fmac_f32_dpp v232, v44, v112 row_shl:1 row_mask:0xf bank_mask:0xf
	v_fmac_f32_dpp v233, v45, v113 row_shl:1 row_mask:0xf bank_mask:0xf
	v_fmac_f32_dpp v234, v34, v102 row_shl:1 row_mask:0xf bank_mask:0xf
	v_fmac_f32_dpp v235, v35, v103 row_shl:1 row_mask:0xf bank_mask:0xf
	v_fmac_f32_dpp v236, v36, v104 row_shl:1 row_mask:0xf bank_mask:0xf
	v_fmac_f32_dpp v237, v37, v105 row_shl:1 row_mask:0xf bank_mask:0xf
	v_fmac_f32_dpp v230, v46, v214 row_ror:1 row_mask:0xf bank_mask:0xf
	v_fmac_f32_dpp v231, v47, v215 row_ror:1 row_mask:0xf bank_mask:0xf
	v_fmac_f32_dpp v232, v48, v216 row_ror:1 row_mask:0xf bank_mask:0xf
	v_fmac_f32_dpp v233, v49, v217 row_ror:1 row_mask:0xf bank_mask:0xf
	v_fmac_f32_dpp v234, v38, v218 row_ror:1 row_mask:0xf bank_mask:0xf
	v_fmac_f32_dpp v235, v39, v219 row_ror:1 row_mask:0xf bank_mask:0xf
	v_fmac_f32_dpp v236, v40, v220 row_ror:1 row_mask:0xf bank_mask:0xf
	v_fmac_f32_dpp v237, v41, v221 row_ror:1 row_mask:0xf bank_mask:0xf
	v_pk_mul_f32 v[174:175], v[230:231], s[34:35]
	v_pk_mul_f32 v[176:177], v[232:233], s[34:35]
	v_exp_f32_e32 v174, v174
	v_exp_f32_e32 v175, v175
	v_exp_f32_e32 v176, v176
	v_exp_f32_e32 v177, v177
	v_pk_add_f32 v[174:175], v[174:175], s[36:37]
	v_pk_add_f32 v[176:177], v[176:177], s[36:37]
	v_rcp_f32_e32 v174, v174
	v_rcp_f32_e32 v175, v175
	v_rcp_f32_e32 v176, v176
	v_rcp_f32_e32 v177, v177
	v_pk_mul_f32 v[174:175], v[230:231], v[174:175]
	v_pk_mul_f32 v[176:177], v[232:233], v[176:177]
	v_pk_mul_f32 v[174:175], v[174:175], v[234:235]
	v_pk_mul_f32 v[176:177], v[176:177], v[236:237]
	v_cvt_pk_bf16_f32 v180, v174, v175
	v_cvt_pk_bf16_f32 v181, v176, v177
	v_add_u32_e32 v239, 0x81000, v238
	s_and_saveexec_b64 s[16:17], s[40:41]
	global_store_dwordx2 v239, v[180:181], s[30:31] offset:8
	s_or_b64 exec, exec, s[16:17]
	v_pk_fma_f32 v[230:231], v[30:31], v[118:119], v[106:107]
	v_pk_fma_f32 v[232:233], v[32:33], v[120:121], v[108:109]
	v_pk_fma_f32 v[234:235], v[22:23], v[114:115], v[98:99]
	v_pk_fma_f32 v[236:237], v[24:25], v[116:117], v[100:101]
	v_fmac_f32_dpp v230, v30, v126 row_shr:1 row_mask:0xf bank_mask:0xf
	v_fmac_f32_dpp v231, v31, v127 row_shr:1 row_mask:0xf bank_mask:0xf
	v_fmac_f32_dpp v232, v32, v128 row_shr:1 row_mask:0xf bank_mask:0xf
	v_fmac_f32_dpp v233, v33, v129 row_shr:1 row_mask:0xf bank_mask:0xf
	v_fmac_f32_dpp v234, v22, v122 row_shr:1 row_mask:0xf bank_mask:0xf
	v_fmac_f32_dpp v235, v23, v123 row_shr:1 row_mask:0xf bank_mask:0xf
	v_fmac_f32_dpp v236, v24, v124 row_shr:1 row_mask:0xf bank_mask:0xf
	v_fmac_f32_dpp v237, v25, v125 row_shr:1 row_mask:0xf bank_mask:0xf
	v_fmac_f32_dpp v230, v30, v110 row_shl:1 row_mask:0xf bank_mask:0xf
	v_fmac_f32_dpp v231, v31, v111 row_shl:1 row_mask:0xf bank_mask:0xf
	v_fmac_f32_dpp v232, v32, v112 row_shl:1 row_mask:0xf bank_mask:0xf
	v_fmac_f32_dpp v233, v33, v113 row_shl:1 row_mask:0xf bank_mask:0xf
	v_fmac_f32_dpp v234, v22, v102 row_shl:1 row_mask:0xf bank_mask:0xf
	v_fmac_f32_dpp v235, v23, v103 row_shl:1 row_mask:0xf bank_mask:0xf
	v_fmac_f32_dpp v236, v24, v104 row_shl:1 row_mask:0xf bank_mask:0xf
	v_fmac_f32_dpp v237, v25, v105 row_shl:1 row_mask:0xf bank_mask:0xf
	v_fmac_f32_dpp v230, v26, v222 row_ror:15 row_mask:0xf bank_mask:0xf
	v_fmac_f32_dpp v231, v27, v223 row_ror:15 row_mask:0xf bank_mask:0xf
	v_fmac_f32_dpp v232, v28, v224 row_ror:15 row_mask:0xf bank_mask:0xf
	v_fmac_f32_dpp v233, v29, v225 row_ror:15 row_mask:0xf bank_mask:0xf
	v_fmac_f32_dpp v234, v18, v226 row_ror:15 row_mask:0xf bank_mask:0xf
	v_fmac_f32_dpp v235, v19, v227 row_ror:15 row_mask:0xf bank_mask:0xf
	v_fmac_f32_dpp v236, v20, v228 row_ror:15 row_mask:0xf bank_mask:0xf
	v_fmac_f32_dpp v237, v21, v229 row_ror:15 row_mask:0xf bank_mask:0xf
	v_pk_mul_f32 v[174:175], v[230:231], s[34:35]
; __device__ __forceinline__ unsigned cvt_pk_bf16(float lo, float hi) { unsigned r; asm volatile("v_cvt_pk_bf16_f32 %0, %1, %2" : "=v"(r) : "v"(lo), "v"(hi)); return r; }
; __device__ __forceinline__ float sigmoid_f(float x) { return fast_rcp(1.0f + fast_exp2(-1.4426950409f * x)); }
;     __device__ __forceinline__ void operator()(f32x4 (&acc)[2][2][4][2], const Unit& u, int wr, int wc, int fr, int fq) const {
;     ...
;                 for (int m = 0; m < 4; ++m) {
;                     f32x4 cv[2];
; #pragma unroll
;                     for (int bj = 0; bj < 2; ++bj) {
;                         const f32x4 cur = acc[ai][bj][m][n], lo = acc[ai][bj][m > 0 ? m - 1 : 0][n], hi = acc[ai][bj][m < 3 ? m + 1 : 3][n];
;                         f32x4 pv, nv;
; #pragma unroll
;                         for (int idx = 0; idx < 4; ++idx) {
;                             const float y = (fr == 15) ? lo[idx] : cur[idx], z = (fr == 0) ? hi[idx] : cur[idx];
;                             pv[idx] = __int_as_float(__builtin_amdgcn_update_dpp(0, __float_as_int(y), 0x121, 0xf, 0xf, false));
;                             nv[idx] = __int_as_float(__builtin_amdgcn_update_dpp(0, __float_as_int(z), 0x12f, 0xf, 0xf, false));
;                         }
;                         cv[bj] = kc[bj][0] * pv + kc[bj][1] * cur + kc[bj][2] * nv + bc[bj];
;                     }
;                     const int row = row0 + ai * HALF + m * 16;
;                     const bool edge = (m == 0 && fr == 0) || (m == 3 && fr == 15);
;                     if (!edge) { const f32x4 gt = cv[0], vl = cv[1];
;                         u32x2 w; w.x = cvt_pk_bf16(gt[0] * sigmoid_f(gt[0]) * vl[0], gt[1] * sigmoid_f(gt[1]) * vl[1]); w.y = cvt_pk_bf16(gt[2] * sigmoid_f(gt[2]) * vl[2], gt[3] * sigmoid_f(gt[3]) * vl[3]);
;                         *(u32x2*)(ACT + (size_t)row * FF + j4) = w; }
	v_pk_mul_f32 v[176:177], v[232:233], s[34:35]
	v_exp_f32_e32 v174, v174
	v_exp_f32_e32 v175, v175
	v_exp_f32_e32 v176, v176
	v_exp_f32_e32 v177, v177
	v_pk_add_f32 v[174:175], v[174:175], s[36:37]
	v_pk_add_f32 v[176:177], v[176:177], s[36:37]
	v_rcp_f32_e32 v174, v174
	v_rcp_f32_e32 v175, v175
	v_rcp_f32_e32 v176, v176
	v_rcp_f32_e32 v177, v177
	v_pk_mul_f32 v[174:175], v[230:231], v[174:175]
	v_pk_mul_f32 v[176:177], v[232:233], v[176:177]
	v_pk_mul_f32 v[174:175], v[174:175], v[234:235]
	v_pk_mul_f32 v[176:177], v[176:177], v[236:237]
	v_cvt_pk_bf16_f32 v180, v174, v175
	v_cvt_pk_bf16_f32 v181, v176, v177
	v_add_u32_e32 v239, 0x158000, v238
	s_and_saveexec_b64 s[16:17], s[44:45]
	global_store_dwordx2 v239, v[180:181], s[30:31] offset:8
	s_or_b64 exec, exec, s[16:17]
	v_pk_fma_f32 v[230:231], v[26:27], v[118:119], v[106:107]
	v_pk_fma_f32 v[232:233], v[28:29], v[120:121], v[108:109]
	v_pk_fma_f32 v[234:235], v[18:19], v[114:115], v[98:99]
	v_pk_fma_f32 v[236:237], v[20:21], v[116:117], v[100:101]
	v_fmac_f32_dpp v230, v26, v126 row_shr:1 row_mask:0xf bank_mask:0xf
	v_fmac_f32_dpp v231, v27, v127 row_shr:1 row_mask:0xf bank_mask:0xf
	v_fmac_f32_dpp v232, v28, v128 row_shr:1 row_mask:0xf bank_mask:0xf
	v_fmac_f32_dpp v233, v29, v129 row_shr:1 row_mask:0xf bank_mask:0xf
	v_fmac_f32_dpp v234, v18, v122 row_shr:1 row_mask:0xf bank_mask:0xf
	v_fmac_f32_dpp v235, v19, v123 row_shr:1 row_mask:0xf bank_mask:0xf
	v_fmac_f32_dpp v236, v20, v124 row_shr:1 row_mask:0xf bank_mask:0xf
	v_fmac_f32_dpp v237, v21, v125 row_shr:1 row_mask:0xf bank_mask:0xf
	v_fmac_f32_dpp v230, v26, v110 row_shl:1 row_mask:0xf bank_mask:0xf
	v_fmac_f32_dpp v231, v27, v111 row_shl:1 row_mask:0xf bank_mask:0xf
	v_fmac_f32_dpp v232, v28, v112 row_shl:1 row_mask:0xf bank_mask:0xf
	v_fmac_f32_dpp v233, v29, v113 row_shl:1 row_mask:0xf bank_mask:0xf
	v_fmac_f32_dpp v234, v18, v102 row_shl:1 row_mask:0xf bank_mask:0xf
	v_fmac_f32_dpp v235, v19, v103 row_shl:1 row_mask:0xf bank_mask:0xf
	v_fmac_f32_dpp v236, v20, v104 row_shl:1 row_mask:0xf bank_mask:0xf
	v_fmac_f32_dpp v237, v21, v105 row_shl:1 row_mask:0xf bank_mask:0xf
	v_fmac_f32_dpp v230, v30, v214 row_ror:1 row_mask:0xf bank_mask:0xf
	v_fmac_f32_dpp v231, v31, v215 row_ror:1 row_mask:0xf bank_mask:0xf
	v_fmac_f32_dpp v232, v32, v216 row_ror:1 row_mask:0xf bank_mask:0xf
	v_fmac_f32_dpp v233, v33, v217 row_ror:1 row_mask:0xf bank_mask:0xf
	v_fmac_f32_dpp v234, v22, v218 row_ror:1 row_mask:0xf bank_mask:0xf
	v_fmac_f32_dpp v235, v23, v219 row_ror:1 row_mask:0xf bank_mask:0xf
	v_fmac_f32_dpp v236, v24, v220 row_ror:1 row_mask:0xf bank_mask:0xf
	v_fmac_f32_dpp v237, v25, v221 row_ror:1 row_mask:0xf bank_mask:0xf
	v_fmac_f32_dpp v230, v14, v222 row_ror:15 row_mask:0xf bank_mask:0xf
	v_fmac_f32_dpp v231, v15, v223 row_ror:15 row_mask:0xf bank_mask:0xf
	v_fmac_f32_dpp v232, v16, v224 row_ror:15 row_mask:0xf bank_mask:0xf
	v_fmac_f32_dpp v233, v17, v225 row_ror:15 row_mask:0xf bank_mask:0xf
	v_fmac_f32_dpp v234, v6, v226 row_ror:15 row_mask:0xf bank_mask:0xf
	v_fmac_f32_dpp v235, v7, v227 row_ror:15 row_mask:0xf bank_mask:0xf
	v_fmac_f32_dpp v236, v8, v228 row_ror:15 row_mask:0xf bank_mask:0xf
	v_fmac_f32_dpp v237, v9, v229 row_ror:15 row_mask:0xf bank_mask:0xf
	v_pk_mul_f32 v[174:175], v[230:231], s[34:35]
	v_pk_mul_f32 v[176:177], v[232:233], s[34:35]
	v_exp_f32_e32 v174, v174
	v_exp_f32_e32 v175, v175
	v_exp_f32_e32 v176, v176
	v_exp_f32_e32 v177, v177
	v_pk_add_f32 v[174:175], v[174:175], s[36:37]
	v_pk_add_f32 v[176:177], v[176:177], s[36:37]
	v_rcp_f32_e32 v174, v174
	v_rcp_f32_e32 v175, v175
	v_rcp_f32_e32 v176, v176
	v_rcp_f32_e32 v177, v177
	v_pk_mul_f32 v[174:175], v[230:231], v[174:175]
	v_pk_mul_f32 v[176:177], v[232:233], v[176:177]
	v_pk_mul_f32 v[174:175], v[174:175], v[234:235]
	v_pk_mul_f32 v[176:177], v[176:177], v[236:237]
	v_cvt_pk_bf16_f32 v178, v174, v175
	v_cvt_pk_bf16_f32 v179, v176, v177
	v_add_u32_e32 v239, 0x183000, v238
	global_store_dwordx2 v239, v[178:179], s[30:31] offset:8
	v_pk_fma_f32 v[230:231], v[14:15], v[118:119], v[106:107]
	v_pk_fma_f32 v[232:233], v[16:17], v[120:121], v[108:109]
	v_pk_fma_f32 v[234:235], v[6:7], v[114:115], v[98:99]
	v_pk_fma_f32 v[236:237], v[8:9], v[116:117], v[100:101]
	v_fmac_f32_dpp v230, v14, v126 row_shr:1 row_mask:0xf bank_mask:0xf
	v_fmac_f32_dpp v231, v15, v127 row_shr:1 row_mask:0xf bank_mask:0xf
	v_fmac_f32_dpp v232, v16, v128 row_shr:1 row_mask:0xf bank_mask:0xf
	v_fmac_f32_dpp v233, v17, v129 row_shr:1 row_mask:0xf bank_mask:0xf
	v_fmac_f32_dpp v234, v6, v122 row_shr:1 row_mask:0xf bank_mask:0xf
	v_fmac_f32_dpp v235, v7, v123 row_shr:1 row_mask:0xf bank_mask:0xf
	v_fmac_f32_dpp v236, v8, v124 row_shr:1 row_mask:0xf bank_mask:0xf
	v_fmac_f32_dpp v237, v9, v125 row_shr:1 row_mask:0xf bank_mask:0xf
	v_fmac_f32_dpp v230, v14, v110 row_shl:1 row_mask:0xf bank_mask:0xf
	v_fmac_f32_dpp v231, v15, v111 row_shl:1 row_mask:0xf bank_mask:0xf
	v_fmac_f32_dpp v232, v16, v112 row_shl:1 row_mask:0xf bank_mask:0xf
; __device__ __forceinline__ unsigned cvt_pk_bf16(float lo, float hi) { unsigned r; asm volatile("v_cvt_pk_bf16_f32 %0, %1, %2" : "=v"(r) : "v"(lo), "v"(hi)); return r; }
; __device__ __forceinline__ float sigmoid_f(float x) { return fast_rcp(1.0f + fast_exp2(-1.4426950409f * x)); }
;     __device__ __forceinline__ void operator()(f32x4 (&acc)[2][2][4][2], const Unit& u, int wr, int wc, int fr, int fq) const {
;     ...
;             for (int ai = 0; ai < 2; ++ai) {
;                 const int grp = u.pm * 4 + ai * 2 + wr;
; #pragma unroll
;                 for (int m = 0; m < 4; ++m) {
;                     f32x4 cv[2];
; #pragma unroll
;                     for (int bj = 0; bj < 2; ++bj) {
;                         const f32x4 cur = acc[ai][bj][m][n], lo = acc[ai][bj][m > 0 ? m - 1 : 0][n], hi = acc[ai][bj][m < 3 ? m + 1 : 3][n];
;                         f32x4 pv, nv;
; #pragma unroll
;                         for (int idx = 0; idx < 4; ++idx) {
;                             const float y = (fr == 15) ? lo[idx] : cur[idx], z = (fr == 0) ? hi[idx] : cur[idx];
;                             pv[idx] = __int_as_float(__builtin_amdgcn_update_dpp(0, __float_as_int(y), 0x121, 0xf, 0xf, false));
;                             nv[idx] = __int_as_float(__builtin_amdgcn_update_dpp(0, __float_as_int(z), 0x12f, 0xf, 0xf, false));
;                         }
;                         cv[bj] = kc[bj][0] * pv + kc[bj][1] * cur + kc[bj][2] * nv + bc[bj];
;                     }
;                     const int row = row0 + ai * HALF + m * 16;
;                     const bool edge = (m == 0 && fr == 0) || (m == 3 && fr == 15);
;                     if (!edge) { const f32x4 gt = cv[0], vl = cv[1];
;                         u32x2 w; w.x = cvt_pk_bf16(gt[0] * sigmoid_f(gt[0]) * vl[0], gt[1] * sigmoid_f(gt[1]) * vl[1]); w.y = cvt_pk_bf16(gt[2] * sigmoid_f(gt[2]) * vl[2], gt[3] * sigmoid_f(gt[3]) * vl[3]);
;                         *(u32x2*)(ACT + (size_t)row * FF + j4) = w; }
	v_fmac_f32_dpp v233, v17, v113 row_shl:1 row_mask:0xf bank_mask:0xf
	v_fmac_f32_dpp v234, v6, v102 row_shl:1 row_mask:0xf bank_mask:0xf
	v_fmac_f32_dpp v235, v7, v103 row_shl:1 row_mask:0xf bank_mask:0xf
	v_fmac_f32_dpp v236, v8, v104 row_shl:1 row_mask:0xf bank_mask:0xf
	v_fmac_f32_dpp v237, v9, v105 row_shl:1 row_mask:0xf bank_mask:0xf
	v_fmac_f32_dpp v230, v26, v214 row_ror:1 row_mask:0xf bank_mask:0xf
	v_fmac_f32_dpp v231, v27, v215 row_ror:1 row_mask:0xf bank_mask:0xf
	v_fmac_f32_dpp v232, v28, v216 row_ror:1 row_mask:0xf bank_mask:0xf
	v_fmac_f32_dpp v233, v29, v217 row_ror:1 row_mask:0xf bank_mask:0xf
	v_fmac_f32_dpp v234, v18, v218 row_ror:1 row_mask:0xf bank_mask:0xf
	v_fmac_f32_dpp v235, v19, v219 row_ror:1 row_mask:0xf bank_mask:0xf
	v_fmac_f32_dpp v236, v20, v220 row_ror:1 row_mask:0xf bank_mask:0xf
	v_fmac_f32_dpp v237, v21, v221 row_ror:1 row_mask:0xf bank_mask:0xf
	v_fmac_f32_dpp v230, v10, v222 row_ror:15 row_mask:0xf bank_mask:0xf
	v_fmac_f32_dpp v231, v11, v223 row_ror:15 row_mask:0xf bank_mask:0xf
	v_fmac_f32_dpp v232, v12, v224 row_ror:15 row_mask:0xf bank_mask:0xf
	v_fmac_f32_dpp v233, v13, v225 row_ror:15 row_mask:0xf bank_mask:0xf
	v_fmac_f32_dpp v234, v2, v226 row_ror:15 row_mask:0xf bank_mask:0xf
	v_fmac_f32_dpp v235, v3, v227 row_ror:15 row_mask:0xf bank_mask:0xf
	v_fmac_f32_dpp v236, v4, v228 row_ror:15 row_mask:0xf bank_mask:0xf
	v_fmac_f32_dpp v237, v5, v229 row_ror:15 row_mask:0xf bank_mask:0xf
	v_pk_mul_f32 v[174:175], v[230:231], s[34:35]
	v_pk_mul_f32 v[176:177], v[232:233], s[34:35]
	v_exp_f32_e32 v174, v174
	v_exp_f32_e32 v175, v175
	v_exp_f32_e32 v176, v176
	v_exp_f32_e32 v177, v177
	v_pk_add_f32 v[174:175], v[174:175], s[36:37]
	v_pk_add_f32 v[176:177], v[176:177], s[36:37]
	v_rcp_f32_e32 v174, v174
	v_rcp_f32_e32 v175, v175
	v_rcp_f32_e32 v176, v176
	v_rcp_f32_e32 v177, v177
	v_pk_mul_f32 v[174:175], v[230:231], v[174:175]
	v_pk_mul_f32 v[176:177], v[232:233], v[176:177]
	v_pk_mul_f32 v[174:175], v[174:175], v[234:235]
	v_pk_mul_f32 v[176:177], v[176:177], v[236:237]
	v_cvt_pk_bf16_f32 v180, v174, v175
	v_cvt_pk_bf16_f32 v181, v176, v177
	v_add_u32_e32 v239, 0x1ae000, v238
	global_store_dwordx2 v239, v[180:181], s[30:31] offset:8
	v_pk_fma_f32 v[230:231], v[10:11], v[118:119], v[106:107]
	v_pk_fma_f32 v[232:233], v[12:13], v[120:121], v[108:109]
	v_pk_fma_f32 v[234:235], v[2:3], v[114:115], v[98:99]
	v_pk_fma_f32 v[236:237], v[4:5], v[116:117], v[100:101]
	v_fmac_f32_dpp v230, v10, v126 row_shr:1 row_mask:0xf bank_mask:0xf
	v_fmac_f32_dpp v231, v11, v127 row_shr:1 row_mask:0xf bank_mask:0xf
	v_fmac_f32_dpp v232, v12, v128 row_shr:1 row_mask:0xf bank_mask:0xf
	v_fmac_f32_dpp v233, v13, v129 row_shr:1 row_mask:0xf bank_mask:0xf
	v_fmac_f32_dpp v234, v2, v122 row_shr:1 row_mask:0xf bank_mask:0xf
	v_fmac_f32_dpp v235, v3, v123 row_shr:1 row_mask:0xf bank_mask:0xf
	v_fmac_f32_dpp v236, v4, v124 row_shr:1 row_mask:0xf bank_mask:0xf
	v_fmac_f32_dpp v237, v5, v125 row_shr:1 row_mask:0xf bank_mask:0xf
	v_fmac_f32_dpp v230, v10, v110 row_shl:1 row_mask:0xf bank_mask:0xf
	v_fmac_f32_dpp v231, v11, v111 row_shl:1 row_mask:0xf bank_mask:0xf
	v_fmac_f32_dpp v232, v12, v112 row_shl:1 row_mask:0xf bank_mask:0xf
	v_fmac_f32_dpp v233, v13, v113 row_shl:1 row_mask:0xf bank_mask:0xf
	v_fmac_f32_dpp v234, v2, v102 row_shl:1 row_mask:0xf bank_mask:0xf
	v_fmac_f32_dpp v235, v3, v103 row_shl:1 row_mask:0xf bank_mask:0xf
	v_fmac_f32_dpp v236, v4, v104 row_shl:1 row_mask:0xf bank_mask:0xf
	v_fmac_f32_dpp v237, v5, v105 row_shl:1 row_mask:0xf bank_mask:0xf
	v_fmac_f32_dpp v230, v14, v214 row_ror:1 row_mask:0xf bank_mask:0xf
	v_fmac_f32_dpp v231, v15, v215 row_ror:1 row_mask:0xf bank_mask:0xf
	v_fmac_f32_dpp v232, v16, v216 row_ror:1 row_mask:0xf bank_mask:0xf
	v_fmac_f32_dpp v233, v17, v217 row_ror:1 row_mask:0xf bank_mask:0xf
	v_fmac_f32_dpp v234, v6, v218 row_ror:1 row_mask:0xf bank_mask:0xf
	v_fmac_f32_dpp v235, v7, v219 row_ror:1 row_mask:0xf bank_mask:0xf
	v_fmac_f32_dpp v236, v8, v220 row_ror:1 row_mask:0xf bank_mask:0xf
	v_fmac_f32_dpp v237, v9, v221 row_ror:1 row_mask:0xf bank_mask:0xf
	v_pk_mul_f32 v[174:175], v[230:231], s[34:35]
	v_pk_mul_f32 v[176:177], v[232:233], s[34:35]
	v_exp_f32_e32 v174, v174
	v_exp_f32_e32 v175, v175
	v_exp_f32_e32 v176, v176
	v_exp_f32_e32 v177, v177
	v_pk_add_f32 v[174:175], v[174:175], s[36:37]
	v_pk_add_f32 v[176:177], v[176:177], s[36:37]
	v_rcp_f32_e32 v174, v174
	v_rcp_f32_e32 v175, v175
	v_rcp_f32_e32 v176, v176
	v_rcp_f32_e32 v177, v177
	v_pk_mul_f32 v[174:175], v[230:231], v[174:175]
	v_pk_mul_f32 v[176:177], v[232:233], v[176:177]
	v_pk_mul_f32 v[174:175], v[174:175], v[234:235]
	v_pk_mul_f32 v[176:177], v[176:177], v[236:237]
	v_cvt_pk_bf16_f32 v178, v174, v175
	v_cvt_pk_bf16_f32 v179, v176, v177
	v_add_u32_e32 v239, 0x1d9000, v238
	s_and_saveexec_b64 s[16:17], s[40:41]
	global_store_dwordx2 v239, v[178:179], s[30:31] offset:8
	s_or_b64 exec, exec, s[16:17]
	s_movk_i32 s94, 0x1000
	s_movk_i32 s95, 0x3000
	s_and_b64 vcc, exec, s[50:51]
	s_mov_b64 s[12:13], -1
	s_cbranch_vccnz .LBB0_746
